# attention prompt loop: V tiles in three rotating LDS buffers, one workgroup barrier per 64-key tile instead of two; sample unit K swizzle fix
# baseline (speedup 1.0000x reference)
.LBB0_698:
	s_or_b64 exec, exec, s[8:9]
	s_waitcnt lgkmcnt(0)
	s_barrier
	ds_read_b32 v1, v175
	s_movk_i32 s8, 0x47f
	s_waitcnt lgkmcnt(0)
	v_cmp_lt_i32_e32 vcc, s8, v1
	v_readfirstlane_b32 s90, v1
	s_mov_b64 s[8:9], -1
	s_cbranch_vccnz .LBB0_693
	s_cmpk_gt_i32 s90, 0x7f
	s_cbranch_scc0 .LBB0_732
	s_add_i32 s8, s90, 0xffffff80
	s_lshr_b32 s8, s8, 6
	v_mov_b32_e32 v80, v226
	s_sub_i32 s10, 15, s8
	s_lshl_b32 s8, s90, 9
	v_ashrrev_i32_e32 v42, 6, v80
	s_and_b32 s12, s8, 0x7000
	s_lshl_b32 s8, s10, 8
	v_lshlrev_b32_e32 v2, 5, v42
	s_or_b32 s60, s8, s12
	v_ashrrev_i32_e32 v3, 31, v2
	v_and_b32_e32 v166, 31, v80
	v_lshl_add_u64 v[168:169], v[2:3], 0, s[60:61]
	s_and_b32 s11, s90, 7
	v_or_b32_e32 v4, v168, v166
	v_mov_b64_e32 v[2:3], s[46:47]
	v_bfe_u32 v1, v80, 5, 1
	v_mad_i64_i32 v[2:3], s[8:9], v4, s77, v[2:3]
	s_mul_i32 s60, s11, 0x180
	v_lshl_add_u64 v[2:3], v[2:3], 0, s[60:61]
	v_lshlrev_b32_e32 v170, 4, v1
	v_mov_b32_e32 v171, v0
	s_lshl_b32 s92, s10, 2
	s_lshl_b32 s8, s12, 11
	v_lshl_add_u64 v[38:39], v[2:3], 0, v[170:171]
	s_add_u32 s9, s69, s8
	global_load_dwordx4 v[2:5], v[38:39], off offset:256
	global_load_dwordx4 v[6:9], v[38:39], off offset:288
	global_load_dwordx4 v[10:13], v[38:39], off offset:320
	global_load_dwordx4 v[14:17], v[38:39], off offset:352
	s_addc_u32 s10, s70, 0
	s_lshl_b32 s60, s11, 7
	s_lshl_b32 s11, s11, 8
	s_add_u32 s14, s9, s11
	s_addc_u32 s15, s10, 0
	s_add_u32 s8, s3, s8
	v_ashrrev_i32_e32 v172, 4, v80
	s_addc_u32 s9, s63, 0
	v_lshlrev_b32_e32 v43, 3, v80
	v_add_u32_e32 v40, 32, v172
	s_add_u32 s64, s8, s11
	v_and_b32_e32 v174, 0x78, v43
	v_ashrrev_i32_e32 v176, 3, v80
	s_addc_u32 s65, s9, 0
	v_ashrrev_i32_e32 v173, 31, v172
	v_ashrrev_i32_e32 v41, 31, v40
	s_lshl_b32 s8, s12, 7
	v_lshlrev_b32_e32 v44, 1, v174
	v_lshlrev_b64 v[52:53], 11, v[172:173]
	v_lshlrev_b64 v[26:27], 11, v[40:41]
	s_add_u32 s8, s67, s8
	v_ashrrev_i32_e32 v177, 31, v176
	v_lshlrev_b32_e32 v81, 4, v80
	v_or_b32_e32 v52, v52, v44
	v_or_b32_e32 v26, v26, v44
	s_addc_u32 s9, s68, 0
	v_lshlrev_b64 v[34:35], 7, v[176:177]
	v_and_b32_e32 v50, 0x70, v81
	v_lshl_add_u64 v[18:19], s[14:15], 0, v[52:53]
	v_lshl_add_u64 v[22:23], s[14:15], 0, v[26:27]
	v_lshl_add_u64 v[28:29], s[64:65], 0, v[52:53]
	v_lshl_add_u64 v[30:31], s[64:65], 0, v[26:27]
	v_lshl_add_u64 v[34:35], s[8:9], 0, v[34:35]
	v_mov_b32_e32 v51, v0
	global_load_dwordx4 v[18:21], v[18:19], off
	v_lshl_add_u64 v[54:55], v[34:35], 0, v[50:51]
	global_load_dwordx4 v[22:25], v[22:23], off
	s_nop 0
	global_load_dwordx4 v[26:29], v[28:29], off
	s_nop 0
	global_load_dwordx4 v[30:33], v[30:31], off
	s_nop 0
	global_load_dwordx4 v[34:37], v[54:55], off
	global_load_dwordx4 v[126:129], v[38:39], off
	global_load_dwordx4 v[122:125], v[38:39], off offset:32
	global_load_dwordx4 v[118:121], v[38:39], off offset:64
	global_load_dwordx4 v[114:117], v[38:39], off offset:96
	global_load_dwordx4 v[110:113], v[38:39], off offset:128
	global_load_dwordx4 v[106:109], v[38:39], off offset:160
	global_load_dwordx4 v[102:105], v[38:39], off offset:192
	global_load_dwordx4 v[98:101], v[38:39], off offset:224
	s_movk_i32 s10, 0x1200
	v_mul_lo_u32 v41, v42, s10
	v_mul_u32_u24_e32 v42, 0x90, v166
	v_add3_u32 v41, s79, v41, v42
	v_add_u32_e32 v183, v41, v170
	v_and_b32_e32 v45, 0xfffff0, v172
	s_movk_i32 s10, 0x70
	v_mul_u32_u24_e32 v64, 0x180, v166
	v_lshlrev_b32_e32 v185, 3, v166
	v_and_b32_e32 v185, 0x70, v185
	v_bitop3_b32 v42, v170, v64, v185 bitop3:0xde
	v_add_u32_e32 v185, 0, v42
	v_or_b32_e32 v56, 64, v170
	v_lshlrev_b32_e32 v188, 3, v166
	v_and_b32_e32 v188, 0x70, v188
	v_bitop3_b32 v60, v56, v64, v188 bitop3:0xde
	v_add_u32_e32 v188, 0, v60
	v_or_b32_e32 v65, 0x60, v170
	v_lshlrev_b32_e32 v187, 3, v166
	v_and_b32_e32 v187, 0x70, v187
	v_bitop3_b32 v68, v65, v64, v187 bitop3:0xde
	v_add_u32_e32 v187, 0, v68
	v_and_b32_e32 v82, 63, v80
	v_ashrrev_i32_e32 v184, 7, v80
	v_add_u32_e32 v193, s92, v184
	s_add_i32 s92, s92, 4
	s_mov_b32 s16, 0
	s_waitcnt vmcnt(16)
	ds_write_b128 v183, v[2:5]
	s_waitcnt vmcnt(15)
	ds_write_b128 v183, v[6:9] offset:32
	s_waitcnt vmcnt(14)
	ds_write_b128 v183, v[10:13] offset:64
	s_waitcnt vmcnt(13)
	ds_write_b128 v183, v[14:17] offset:96
	v_lshlrev_b32_e32 v2, 1, v172
	v_and_b32_e32 v6, 0xfffff0, v40
	v_lshlrev_b32_e32 v7, 1, v40
	v_and_or_b32 v2, v2, 8, v45
	v_and_or_b32 v6, v7, 8, v6
	v_lshrrev_b32_e32 v3, 1, v172
	v_lshrrev_b32_e32 v2, 1, v2
	v_bfe_u32 v4, v43, 5, 2
	v_and_b32_e32 v5, 3, v172
	v_lshrrev_b32_e32 v6, 1, v6
	v_or_b32_e32 v2, v2, v4
	v_and_or_b32 v3, v3, 4, v5
	v_or_b32_e32 v4, v6, v4
	v_lshlrev_b32_e32 v2, 9, v2
	v_lshlrev_b32_e32 v3, 6, v3
	v_and_b32_e32 v5, 48, v44
	v_lshlrev_b32_e32 v4, 9, v4
	v_or3_b32 v2, v2, v3, v5
	v_or3_b32 v3, v4, v3, v5
	v_add_u32_e32 v189, 0, v2
	v_add_u32_e32 v190, 0, v3
	v_mul_lo_u32 v2, v172, s78
	v_lshrrev_b32_e32 v4, 1, v80
	v_bitop3_b32 v3, v44, v4, s10 bitop3:0x78
	v_lshlrev_b32_e32 v4, 3, v176
	v_add3_u32 v191, v3, v2, 0
	v_mul_lo_u32 v2, v176, s78
	v_or_b32_e32 v3, 0x100, v50
	v_and_b32_e32 v4, 0x70, v4
	v_xad_u32 v2, v3, v4, v2
	v_add_u32_e32 v192, 0, v2
	s_waitcnt vmcnt(0)
	v_or_b32_e32 v10, 32, v170
	v_lshlrev_b32_e32 v186, 3, v166
	v_and_b32_e32 v186, 0x70, v186
	v_bitop3_b32 v14, v10, v64, v186 bitop3:0xde
	v_add_u32_e32 v186, 0, v14
	s_waitcnt vmcnt(12)
	ds_write_b128 v189, v[18:21]
	s_mov_b64 s[10:11], 0x20000
	s_waitcnt vmcnt(11)
	ds_write_b128 v190, v[22:25]
	s_waitcnt vmcnt(10)
	ds_write_b128 v191, v[26:29] offset:32768
	s_waitcnt vmcnt(9)
	ds_write_b128 v191, v[30:33] offset:45056
	s_waitcnt vmcnt(8)
	ds_write_b128 v192, v[34:37] offset:32768
	s_waitcnt lgkmcnt(0)
	s_barrier
	ds_read_b128 v[2:5], v185 offset:32768
	ds_read_b128 v[6:9], v185 offset:32896
	s_waitcnt vmcnt(7) lgkmcnt(1)
	v_mfma_f32_32x32x16_bf16 v[18:33], v[2:5], v[126:129], 0
	ds_read_b128 v[2:5], v185 offset:45056
	ds_read_b128 v[10:13], v185 offset:33024
	s_mov_b32 s17, s16
	s_mov_b32 s18, s16
	s_mov_b32 s19, s16
	s_mov_b32 s20, s16
	s_mov_b32 s21, s16
	s_waitcnt lgkmcnt(1)
	v_mfma_f32_32x32x16_bf16 v[34:49], v[2:5], v[126:129], 0
	ds_read_b128 v[2:5], v186 offset:32768
	ds_read_b128 v[14:17], v186 offset:32896
	ds_read_b128 v[56:59], v186 offset:33024
	s_mov_b32 s22, s16
	s_mov_b32 s23, s16
	s_mov_b32 s24, s16
	s_mov_b32 s25, s16
	s_mov_b32 s26, s16
	s_waitcnt vmcnt(6) lgkmcnt(2)
	v_mfma_f32_32x32x16_bf16 v[18:33], v[2:5], v[122:125], v[18:33]
	ds_read_b128 v[2:5], v186 offset:45056
	s_mov_b32 s27, s16
	s_mov_b32 s28, s16
	s_mov_b32 s29, s16
	s_mov_b32 s30, s16
	s_mov_b32 s31, s16
	v_add_u32_e32 v194, 0x3000, v191
	s_waitcnt lgkmcnt(0)
	v_mfma_f32_32x32x16_bf16 v[34:49], v[2:5], v[122:125], v[34:49]
	ds_read_b128 v[2:5], v188 offset:32768
	ds_read_b128 v[60:63], v188 offset:32896
	ds_read_b128 v[64:67], v188 offset:33024
	v_lshl_add_u64 v[178:179], s[8:9], 0, v[50:51]
	s_mov_b32 s91, 2
	v_add_u32_e32 v200, 1, v193
	v_cmp_gt_u32_e64 s[8:9], 32, v82
	v_add_u32_e32 v198, 0xe000, v185
	s_waitcnt vmcnt(5) lgkmcnt(2)
	v_mfma_f32_32x32x16_bf16 v[18:33], v[2:5], v[118:121], v[18:33]
	ds_read_b128 v[2:5], v188 offset:45056
	v_add_u32_e32 v196, 0xe000, v186
	v_add_u32_e32 v197, 0xe000, v188
	v_add_u32_e32 v195, 0xe000, v187
	v_mov_b32_e32 v173, 0
	s_waitcnt lgkmcnt(0)
	v_mfma_f32_32x32x16_bf16 v[34:49], v[2:5], v[118:121], v[34:49]
	ds_read_b128 v[2:5], v187 offset:32768
	ds_read_b128 v[68:71], v187 offset:32896
	s_waitcnt vmcnt(4) lgkmcnt(1)
	v_mfma_f32_32x32x16_bf16 v[18:33], v[2:5], v[114:117], v[18:33]
	ds_read_b128 v[2:5], v187 offset:45056
	ds_read_b128 v[72:75], v187 offset:33024
	s_waitcnt lgkmcnt(1)
	v_mfma_f32_32x32x16_bf16 v[34:49], v[2:5], v[114:117], v[34:49]
	s_waitcnt vmcnt(3)
	v_mfma_f32_32x32x16_bf16 v[18:33], v[6:9], v[110:113], v[18:33]
	ds_read_b128 v[2:5], v185 offset:45184
	ds_read_b128 v[6:9], v185 offset:45312
	s_waitcnt lgkmcnt(1)
	v_mfma_f32_32x32x16_bf16 v[34:49], v[2:5], v[110:113], v[34:49]
	s_waitcnt vmcnt(2)
	v_mfma_f32_32x32x16_bf16 v[18:33], v[14:17], v[106:109], v[18:33]
	ds_read_b128 v[2:5], v186 offset:45184
	ds_read_b128 v[14:17], v186 offset:45312
	s_waitcnt lgkmcnt(1)
	v_mfma_f32_32x32x16_bf16 v[34:49], v[2:5], v[106:109], v[34:49]
	s_waitcnt vmcnt(1)
	v_mfma_f32_32x32x16_bf16 v[18:33], v[60:63], v[102:105], v[18:33]
	ds_read_b128 v[2:5], v188 offset:45184
	ds_read_b128 v[60:63], v188 offset:45312
	s_waitcnt lgkmcnt(1)
	v_mfma_f32_32x32x16_bf16 v[34:49], v[2:5], v[102:105], v[34:49]
	s_waitcnt vmcnt(0)
	v_mfma_f32_32x32x16_bf16 v[18:33], v[68:71], v[98:101], v[18:33]
	ds_read_b128 v[2:5], v187 offset:45184
	ds_read_b128 v[68:71], v187 offset:45312
	s_waitcnt lgkmcnt(1)
	v_mfma_f32_32x32x16_bf16 v[34:49], v[2:5], v[98:101], v[34:49]
	ds_read_b128 v[2:5], v183
	ds_read_b128 v[76:79], v183 offset:32
	s_waitcnt lgkmcnt(1)
	v_mfma_f32_32x32x16_bf16 v[18:33], v[10:13], v[2:5], v[18:33]
	v_mfma_f32_32x32x16_bf16 v[34:49], v[6:9], v[2:5], v[34:49]
	v_and_b32_e32 v2, 0x3fffffc0, v80
	v_lshl_add_u32 v167, v2, 2, s76
	v_lshlrev_b32_e32 v6, 3, v82
	v_and_b32_e32 v2, 0xc0, v81
	v_and_or_b32 v7, v6, 24, v2
	ds_read_b128 v[2:5], v183 offset:64
	v_lshlrev_b32_e32 v8, 1, v80
	s_waitcnt lgkmcnt(1)
	v_mfma_f32_32x32x16_bf16 v[18:33], v[56:59], v[76:79], v[18:33]
	ds_read_b128 v[56:59], v183 offset:96
	v_and_b32_e32 v8, 32, v8
	v_and_b32_e32 v6, 0x100, v6
	v_lshl_add_u32 v171, v166, 2, v167
	v_mfma_f32_32x32x16_bf16 v[34:49], v[14:17], v[76:79], v[34:49]
	v_or3_b32 v76, v7, v8, v6
	v_add_u32_e32 v182, 0, v76
	v_add_u32_e32 v177, s81, v76
	s_waitcnt lgkmcnt(1)
	v_mfma_f32_32x32x16_bf16 v[18:33], v[64:67], v[2:5], v[18:33]
	v_lshl_add_u64 v[64:65], v[52:53], 0, s[10:11]
	s_mov_b64 s[10:11], 0x30000
	v_lshl_add_u64 v[52:53], v[52:53], 0, s[10:11]
	s_movk_i32 s10, 0x2000
	v_mfma_f32_32x32x16_bf16 v[34:49], v[60:63], v[2:5], v[34:49]
	v_lshl_add_u64 v[60:61], s[14:15], 0, v[52:53]
	v_lshl_add_u64 v[52:53], s[64:65], 0, v[52:53]
	v_mov_b64_e32 v[2:3], s[16:17]
	v_mov_b64_e32 v[16:17], s[30:31]
	v_mov_b64_e32 v[4:5], s[18:19]
	v_mov_b64_e32 v[6:7], s[20:21]
	v_mov_b64_e32 v[8:9], s[22:23]
	s_waitcnt lgkmcnt(0)
	v_mfma_f32_32x32x16_bf16 v[18:33], v[72:75], v[56:59], v[18:33]
	v_mov_b64_e32 v[10:11], s[24:25]
	v_mov_b64_e32 v[12:13], s[26:27]
	v_mov_b64_e32 v[14:15], s[28:29]
	v_mfma_f32_32x32x16_bf16 v[34:49], v[68:71], v[56:59], v[34:49]
	v_lshl_add_u64 v[56:57], s[14:15], 0, v[64:65]
	v_lshl_add_u64 v[64:65], s[64:65], 0, v[64:65]
	global_load_dwordx4 v[56:59], v[56:57], off
	s_nop 0
	global_load_dwordx4 v[60:63], v[60:61], off
	s_nop 0
	global_load_dwordx4 v[64:67], v[64:65], off
	s_nop 0
	global_load_dwordx4 v[68:71], v[52:53], off
	v_add_co_u32_e32 v52, vcc, s10, v54
	v_max_f32_e32 v72, v19, v19
	s_nop 0
	v_addc_co_u32_e32 v53, vcc, 0, v55, vcc
	global_load_dwordx4 v[52:55], v[52:53], off
	v_max_f32_e32 v73, v18, v18
	v_max_f32_e32 v72, v73, v72
	v_max3_f32 v72, v72, v20, v21
	v_max3_f32 v72, v72, v22, v23
	v_max3_f32 v72, v72, v24, v25
	v_max3_f32 v72, v72, v26, v27
	v_max3_f32 v72, v72, v28, v29
	v_max3_f32 v72, v72, v30, v31
	v_max3_f32 v72, v72, v32, v33
	v_max3_f32 v72, v72, v34, v35
	v_max3_f32 v72, v72, v36, v37
	v_max3_f32 v72, v72, v38, v39
	v_max3_f32 v72, v72, v40, v41
	v_max3_f32 v72, v72, v42, v43
	v_max3_f32 v72, v72, v44, v45
	v_max3_f32 v72, v72, v46, v47
	v_max3_f32 v72, v72, v48, v49
	v_mov_b32_e32 v73, v72
	s_nop 1
	v_permlane32_swap_b32_e32 v72, v73
	v_max_f32_e32 v73, v73, v73
	v_max_f32_e32 v72, v72, v72
	v_max_f32_e32 v72, v72, v73
	v_add_f32_e32 v73, 0x7149f2ca, v72
	v_max_f32_e32 v72, 0xf149f2ca, v72
	v_cmp_ge_f32_e32 vcc, s80, v73
	v_sub_f32_e32 v73, 0xf149f2ca, v72
	v_mul_f32_e32 v73, 0x3dd53b94, v73
	v_exp_f32_e32 v73, v73
	s_cmp_eq_u64 vcc, exec
	s_cselect_b64 vcc, -1, 0
	v_cndmask_b32_e32 v201, v72, v180, vcc
	v_mul_f32_e32 v72, 0xbdd53b94, v201
	v_cndmask_b32_e64 v199, v73, 1.0, vcc
	v_mov_b32_e32 v73, v72
	v_fmamk_f32 v18, v18, 0x3dd53b94, v72
	v_fmamk_f32 v19, v19, 0x3dd53b94, v72
	v_fmamk_f32 v20, v20, 0x3dd53b94, v72
	v_fmamk_f32 v21, v21, 0x3dd53b94, v72
	v_fmamk_f32 v22, v22, 0x3dd53b94, v72
	v_fmamk_f32 v23, v23, 0x3dd53b94, v72
	v_fmamk_f32 v24, v24, 0x3dd53b94, v72
	v_fmamk_f32 v25, v25, 0x3dd53b94, v72
	v_fmamk_f32 v26, v26, 0x3dd53b94, v72
	v_fmamk_f32 v27, v27, 0x3dd53b94, v72
	v_fmamk_f32 v28, v28, 0x3dd53b94, v72
	v_fmamk_f32 v29, v29, 0x3dd53b94, v72
	v_fmamk_f32 v30, v30, 0x3dd53b94, v72
	v_fmamk_f32 v31, v31, 0x3dd53b94, v72
	v_fmamk_f32 v32, v32, 0x3dd53b94, v72
	v_fmac_f32_e32 v73, 0x3dd53b94, v33
	v_exp_f32_e32 v146, v18
	v_exp_f32_e32 v147, v19
	v_exp_f32_e32 v148, v20
	v_exp_f32_e32 v149, v21
	v_exp_f32_e32 v154, v22
	v_exp_f32_e32 v160, v23
	v_exp_f32_e32 v161, v24
	v_exp_f32_e32 v162, v25
	v_exp_f32_e32 v151, v26
	v_exp_f32_e32 v152, v27
	v_exp_f32_e32 v153, v28
	v_exp_f32_e32 v155, v29
	v_exp_f32_e32 v156, v30
	v_exp_f32_e32 v157, v31
	v_exp_f32_e32 v158, v32
	v_exp_f32_e32 v159, v73
	s_waitcnt vmcnt(0)
	v_pk_fma_f32 v[140:141], v[48:49], s[62:63], v[72:73] op_sel_hi:[1,0,0]
	v_pk_fma_f32 v[142:143], v[46:47], s[62:63], v[72:73] op_sel_hi:[1,0,0]
	v_pk_fma_f32 v[144:145], v[44:45], s[62:63], v[72:73] op_sel_hi:[1,0,0]
	v_pk_fma_f32 v[130:131], v[42:43], s[62:63], v[72:73] op_sel_hi:[1,0,0]
	v_pk_fma_f32 v[132:133], v[40:41], s[62:63], v[72:73] op_sel_hi:[1,0,0]
	v_pk_fma_f32 v[134:135], v[38:39], s[62:63], v[72:73] op_sel_hi:[1,0,0]
	v_pk_fma_f32 v[136:137], v[36:37], s[62:63], v[72:73] op_sel_hi:[1,0,0]
	v_pk_fma_f32 v[138:139], v[34:35], s[62:63], v[72:73] op_sel_hi:[1,0,0]
	s_waitcnt vmcnt(4)
	ds_write_b128 v189, v[56:59] offset:16384
	s_waitcnt vmcnt(3)
	ds_write_b128 v190, v[60:63] offset:16384
	s_waitcnt vmcnt(2)
	ds_write_b128 v191, v[64:67] offset:57344
	s_waitcnt vmcnt(1)
	ds_write_b128 v194, v[68:71] offset:57344
	s_waitcnt vmcnt(0)
	ds_write_b128 v192, v[52:55] offset:57344
	v_mov_b64_e32 v[64:65], v[16:17]
	v_mov_b64_e32 v[48:49], v[16:17]
	v_mov_b64_e32 v[32:33], v[16:17]
	v_mov_b64_e32 v[62:63], v[14:15]
	v_mov_b64_e32 v[60:61], v[12:13]
	v_mov_b64_e32 v[58:59], v[10:11]
	v_mov_b64_e32 v[56:57], v[8:9]
	v_mov_b64_e32 v[54:55], v[6:7]
	v_mov_b64_e32 v[52:53], v[4:5]
	v_mov_b64_e32 v[50:51], v[2:3]
	v_mov_b64_e32 v[46:47], v[14:15]
	v_mov_b64_e32 v[44:45], v[12:13]
	v_mov_b64_e32 v[42:43], v[10:11]
	v_mov_b64_e32 v[40:41], v[8:9]
	v_mov_b64_e32 v[38:39], v[6:7]
	v_mov_b64_e32 v[36:37], v[4:5]
	v_mov_b64_e32 v[34:35], v[2:3]
	v_mov_b64_e32 v[30:31], v[14:15]
	v_mov_b64_e32 v[28:29], v[12:13]
	v_mov_b64_e32 v[26:27], v[10:11]
	v_mov_b64_e32 v[24:25], v[8:9]
	v_mov_b64_e32 v[22:23], v[6:7]
	v_mov_b64_e32 v[20:21], v[4:5]
	v_mov_b64_e32 v[18:19], v[2:3]
	s_waitcnt lgkmcnt(0)
	s_barrier
	s_mov_b32 s98, 0
.LBB0_701:
	s_cmp_eq_u32 s98, 0x4000
	s_cselect_b32 s99, 0x1d800, 0
	s_cmp_eq_u32 s98, 0
	s_cselect_b32 s99, 0x4000, s99
	s_cmp_eq_u32 s99, 0x4000
	s_cselect_b32 s100, 0x1d800, 0
	s_cmp_eq_u32 s99, 0
	s_cselect_b32 s100, 0x4000, s100
	v_add_u32_e32 v255, s98, v182
	v_add_u32_e32 v253, s100, v189
	v_add_u32_e32 v254, s100, v190
	s_add_i32 s17, s91, -1
	v_cmp_le_i32_e64 s[10:11], s17, v193
	v_mov_b32_e32 v66, 0xf149f2ca
	v_mov_b32_e32 v67, 0xf149f2ca
	v_mov_b32_e32 v68, 0xf149f2ca
	v_mov_b32_e32 v69, 0xf149f2ca
	v_mov_b32_e32 v70, 0xf149f2ca
	v_mov_b32_e32 v71, 0xf149f2ca
	v_mov_b32_e32 v72, 0xf149f2ca
	v_mov_b32_e32 v73, 0xf149f2ca
	v_mov_b32_e32 v74, 0xf149f2ca
	v_mov_b32_e32 v75, 0xf149f2ca
	v_mov_b32_e32 v76, 0xf149f2ca
	v_mov_b32_e32 v77, 0xf149f2ca
	v_mov_b32_e32 v78, 0xf149f2ca
	v_mov_b32_e32 v79, 0xf149f2ca
	v_mov_b32_e32 v80, 0xf149f2ca
	v_mov_b32_e32 v81, 0xf149f2ca
	v_mov_b32_e32 v82, 0xf149f2ca
	v_mov_b32_e32 v83, 0xf149f2ca
	v_mov_b32_e32 v84, 0xf149f2ca
	v_mov_b32_e32 v85, 0xf149f2ca
	v_mov_b32_e32 v86, 0xf149f2ca
	v_mov_b32_e32 v87, 0xf149f2ca
	v_mov_b32_e32 v88, 0xf149f2ca
	v_mov_b32_e32 v89, 0xf149f2ca
	v_mov_b32_e32 v90, 0xf149f2ca
	v_mov_b32_e32 v91, 0xf149f2ca
	v_mov_b32_e32 v92, 0xf149f2ca
	v_mov_b32_e32 v93, 0xf149f2ca
	v_mov_b32_e32 v94, 0xf149f2ca
	v_mov_b32_e32 v95, 0xf149f2ca
	v_mov_b32_e32 v96, 0xf149f2ca
	v_mov_b32_e32 v97, 0xf149f2ca
	s_and_saveexec_b64 s[12:13], s[10:11]
	s_cbranch_execz .LBB0_703
	ds_read_b128 v[202:205], v185 offset:57344
	ds_read_b128 v[206:209], v198 offset:12288
	ds_read_b128 v[210:213], v186 offset:57344
	ds_read_b128 v[214:217], v196 offset:12288
	ds_read_b128 v[218:221], v188 offset:57344
	ds_read_b128 v[222:225], v197 offset:12288
	s_waitcnt lgkmcnt(5)
	v_mfma_f32_32x32x16_bf16 v[82:97], v[202:205], v[126:129], 0
	ds_read_b128 v[228:231], v187 offset:57344
	s_waitcnt lgkmcnt(5)
	v_mfma_f32_32x32x16_bf16 v[66:81], v[206:209], v[126:129], 0
	ds_read_b128 v[202:205], v195 offset:12288
	s_waitcnt lgkmcnt(5)
	v_mfma_f32_32x32x16_bf16 v[82:97], v[210:213], v[122:125], v[82:97]
	ds_read_b128 v[206:209], v185 offset:57472
	s_waitcnt lgkmcnt(5)
	v_mfma_f32_32x32x16_bf16 v[66:81], v[214:217], v[122:125], v[66:81]
	ds_read_b128 v[210:213], v198 offset:12416
	s_waitcnt lgkmcnt(5)
	v_mfma_f32_32x32x16_bf16 v[82:97], v[218:221], v[118:121], v[82:97]
	ds_read_b128 v[214:217], v186 offset:57472
	s_waitcnt lgkmcnt(5)
	v_mfma_f32_32x32x16_bf16 v[66:81], v[222:225], v[118:121], v[66:81]
	ds_read_b128 v[218:221], v196 offset:12416
	s_waitcnt lgkmcnt(5)
	v_mfma_f32_32x32x16_bf16 v[82:97], v[228:231], v[114:117], v[82:97]
	ds_read_b128 v[222:225], v188 offset:57472
	s_waitcnt lgkmcnt(5)
	v_mfma_f32_32x32x16_bf16 v[66:81], v[202:205], v[114:117], v[66:81]
	ds_read_b128 v[228:231], v197 offset:12416
	ds_read_b128 v[232:235], v183
	s_waitcnt lgkmcnt(6)
	v_mfma_f32_32x32x16_bf16 v[82:97], v[206:209], v[110:113], v[82:97]
	ds_read_b128 v[202:205], v187 offset:57472
	s_waitcnt lgkmcnt(6)
	v_mfma_f32_32x32x16_bf16 v[66:81], v[210:213], v[110:113], v[66:81]
	ds_read_b128 v[206:209], v195 offset:12416
	ds_read_b128 v[236:239], v183 offset:32
	s_waitcnt lgkmcnt(7)
	v_mfma_f32_32x32x16_bf16 v[82:97], v[214:217], v[106:109], v[82:97]
	ds_read_b128 v[210:213], v185 offset:57600
	s_waitcnt lgkmcnt(7)
	v_mfma_f32_32x32x16_bf16 v[66:81], v[218:221], v[106:109], v[66:81]
	ds_read_b128 v[214:217], v198 offset:12544
	ds_read_b128 v[240:243], v183 offset:64
	s_waitcnt lgkmcnt(8)
	v_mfma_f32_32x32x16_bf16 v[82:97], v[222:225], v[102:105], v[82:97]
	ds_read_b128 v[218:221], v186 offset:57600
	s_waitcnt lgkmcnt(8)
	v_mfma_f32_32x32x16_bf16 v[66:81], v[228:231], v[102:105], v[66:81]
	ds_read_b128 v[222:225], v196 offset:12544
	s_waitcnt lgkmcnt(7)
	v_mfma_f32_32x32x16_bf16 v[82:97], v[202:205], v[98:101], v[82:97]
	ds_read_b128 v[228:231], v188 offset:57600
	s_waitcnt lgkmcnt(7)
	v_mfma_f32_32x32x16_bf16 v[66:81], v[206:209], v[98:101], v[66:81]
	ds_read_b128 v[202:205], v197 offset:12544
	s_waitcnt lgkmcnt(6)
	v_mfma_f32_32x32x16_bf16 v[82:97], v[210:213], v[232:235], v[82:97]
	ds_read_b128 v[206:209], v187 offset:57600
	s_waitcnt lgkmcnt(6)
	v_mfma_f32_32x32x16_bf16 v[66:81], v[214:217], v[232:235], v[66:81]
	ds_read_b128 v[210:213], v195 offset:12544
	ds_read_b128 v[232:235], v183 offset:96
	s_waitcnt lgkmcnt(6)
	v_mfma_f32_32x32x16_bf16 v[82:97], v[218:221], v[236:239], v[82:97]
	s_waitcnt lgkmcnt(5)
	v_mfma_f32_32x32x16_bf16 v[66:81], v[222:225], v[236:239], v[66:81]
	s_waitcnt lgkmcnt(4)
	v_mfma_f32_32x32x16_bf16 v[82:97], v[228:231], v[240:243], v[82:97]
	s_waitcnt lgkmcnt(3)
	v_mfma_f32_32x32x16_bf16 v[66:81], v[202:205], v[240:243], v[66:81]
	s_waitcnt lgkmcnt(0)
	v_mfma_f32_32x32x16_bf16 v[82:97], v[206:209], v[232:235], v[82:97]
	s_waitcnt lgkmcnt(0)
	v_mfma_f32_32x32x16_bf16 v[66:81], v[210:213], v[232:235], v[66:81]
.LBB0_703:
	s_or_b64 exec, exec, s[12:13]
	v_add_f32_e32 v150, 0, v146
	v_add_f32_e32 v150, v147, v150
	v_add_f32_e32 v150, v148, v150
	v_add_f32_e32 v150, v149, v150
	v_add_f32_e32 v150, v154, v150
	v_add_f32_e32 v150, v160, v150
	v_add_f32_e32 v150, v161, v150
	v_add_f32_e32 v150, v162, v150
	v_add_f32_e32 v150, v151, v150
	v_add_f32_e32 v150, v152, v150
	v_add_f32_e32 v150, v153, v150
	v_add_f32_e32 v150, v155, v150
	v_exp_f32_e32 v138, v138
	v_add_f32_e32 v150, v156, v150
	v_exp_f32_e32 v139, v139
	v_add_f32_e32 v150, v157, v150
	v_exp_f32_e32 v136, v136
	v_add_f32_e32 v150, v158, v150
	v_exp_f32_e32 v137, v137
	v_add_f32_e32 v150, v159, v150
	v_exp_f32_e32 v134, v134
	v_add_f32_e32 v150, v138, v150
	v_exp_f32_e32 v135, v135
	v_add_f32_e32 v150, v139, v150
	v_exp_f32_e32 v132, v132
	v_add_f32_e32 v150, v136, v150
	v_exp_f32_e32 v133, v133
	v_add_f32_e32 v150, v137, v150
	v_exp_f32_e32 v130, v130
	v_add_f32_e32 v150, v134, v150
	v_exp_f32_e32 v131, v131
	v_add_f32_e32 v150, v135, v150
	v_exp_f32_e32 v144, v144
	v_add_f32_e32 v150, v132, v150
	v_exp_f32_e32 v145, v145
	v_add_f32_e32 v150, v133, v150
	v_exp_f32_e32 v142, v142
	v_add_f32_e32 v150, v130, v150
	v_exp_f32_e32 v143, v143
	v_add_f32_e32 v150, v131, v150
	v_exp_f32_e32 v140, v140
	v_add_f32_e32 v150, v144, v150
	v_exp_f32_e32 v141, v141
	v_add_f32_e32 v150, v145, v150
	v_add_f32_e32 v150, v142, v150
	v_add_f32_e32 v150, v143, v150
	v_add_f32_e32 v150, v140, v150
	v_add_f32_e32 v202, v141, v150
	v_mov_b32_e32 v203, v202
	v_cvt_pk_bf16_f32 v146, v146, v147
	v_cvt_pk_bf16_f32 v147, v148, v149
	v_cvt_pk_bf16_f32 v148, v154, v160
	v_cvt_pk_bf16_f32 v149, v161, v162
	v_cvt_pk_bf16_f32 v154, v151, v152
	v_cvt_pk_bf16_f32 v155, v153, v155
	v_cvt_pk_bf16_f32 v156, v156, v157
	v_cvt_pk_bf16_f32 v157, v158, v159
	v_cvt_pk_bf16_f32 v158, v138, v139
	v_cvt_pk_bf16_f32 v159, v136, v137
	v_cvt_pk_bf16_f32 v160, v134, v135
	v_cvt_pk_bf16_f32 v161, v132, v133
	v_cvt_pk_bf16_f32 v162, v130, v131
	v_cvt_pk_bf16_f32 v163, v144, v145
	v_cvt_pk_bf16_f32 v164, v142, v143
	v_cvt_pk_bf16_f32 v165, v140, v141
	v_permlane32_swap_b32_e32 v202, v203
	v_permlane32_swap_b32_e32 v146, v148
	v_permlane32_swap_b32_e32 v147, v149
	v_permlane32_swap_b32_e32 v154, v156
	v_permlane32_swap_b32_e32 v155, v157
	v_permlane32_swap_b32_e32 v158, v160
	v_permlane32_swap_b32_e32 v159, v161
	v_permlane32_swap_b32_e32 v162, v164
	v_permlane32_swap_b32_e32 v163, v165
	v_add_u32_e32 v205, s16, v172
	v_add_u32_e32 v130, 0x80, v205
	v_add_u32_e32 v132, 0xa0, v205
	v_add_u32_e32 v207, s16, v176
	v_ashrrev_i32_e32 v131, 31, v130
	v_ashrrev_i32_e32 v133, 31, v132
	v_add_u32_e32 v150, 0x80, v207
	v_lshlrev_b64 v[138:139], 11, v[130:131]
	v_lshlrev_b32_e32 v206, 1, v174
	v_lshlrev_b64 v[140:141], 11, v[132:133]
	v_ashrrev_i32_e32 v151, 31, v150
	v_or_b32_e32 v138, v138, v206
	v_or_b32_e32 v140, v140, v206
	v_lshlrev_b64 v[150:151], 7, v[150:151]
	v_lshl_add_u64 v[130:131], s[14:15], 0, v[138:139]
	v_lshl_add_u64 v[134:135], s[14:15], 0, v[140:141]
	v_lshl_add_u64 v[138:139], s[64:65], 0, v[138:139]
	v_lshl_add_u64 v[142:143], s[64:65], 0, v[140:141]
	v_lshl_add_u64 v[150:151], v[178:179], 0, v[150:151]
	global_load_dwordx4 v[130:133], v[130:131], off
	s_nop 0
	global_load_dwordx4 v[134:137], v[134:135], off
	s_nop 0
	global_load_dwordx4 v[138:141], v[138:139], off
	s_nop 0
	global_load_dwordx4 v[142:145], v[142:143], off
	s_nop 0
	global_load_dwordx4 v[150:153], v[150:151], off
	v_cmp_le_i32_e32 vcc, s17, v200
	s_and_saveexec_b64 s[12:13], vcc
	s_cbranch_execz .LBB0_705
	ds_read_b64_tr_b16 v[208:209], v255 offset:0
	ds_read_b64_tr_b16 v[210:211], v255 offset:0x800
	ds_read_b64_tr_b16 v[212:213], v255 offset:0x1000
	ds_read_b64_tr_b16 v[214:215], v255 offset:0x1800
	ds_read_b64_tr_b16 v[216:217], v255 offset:0x2000
	ds_read_b64_tr_b16 v[218:219], v255 offset:0x2800
	ds_read_b64_tr_b16 v[220:221], v255 offset:0x3000
	ds_read_b64_tr_b16 v[222:223], v255 offset:0x3800
	s_waitcnt lgkmcnt(0)
	s_nop 0
	v_mfma_f32_32x32x16_bf16 v[2:17], v[146:149], v[208:211], v[2:17]
	ds_read_b64_tr_b16 v[208:209], v255 offset:0x200
	ds_read_b64_tr_b16 v[210:211], v255 offset:0xa00
	v_mfma_f32_32x32x16_bf16 v[2:17], v[154:157], v[212:215], v[2:17]
	ds_read_b64_tr_b16 v[212:213], v255 offset:0x1200
	ds_read_b64_tr_b16 v[214:215], v255 offset:0x1a00
	v_mfma_f32_32x32x16_bf16 v[2:17], v[158:161], v[216:219], v[2:17]
	ds_read_b64_tr_b16 v[216:217], v255 offset:0x2200
	ds_read_b64_tr_b16 v[218:219], v255 offset:0x2a00
	ds_read_b64_tr_b16 v[228:229], v255 offset:0x3200
	ds_read_b64_tr_b16 v[230:231], v255 offset:0x3a00
	s_waitcnt lgkmcnt(0)
	v_mfma_f32_32x32x16_bf16 v[2:17], v[162:165], v[220:223], v[2:17]
	v_mfma_f32_32x32x16_bf16 v[50:65], v[146:149], v[208:211], v[50:65]
	ds_read_b64_tr_b16 v[208:209], v255 offset:0x400
	ds_read_b64_tr_b16 v[210:211], v255 offset:0xc00
	v_mfma_f32_32x32x16_bf16 v[50:65], v[154:157], v[212:215], v[50:65]
	ds_read_b64_tr_b16 v[212:213], v255 offset:0x1400
	ds_read_b64_tr_b16 v[214:215], v255 offset:0x1c00
	v_mfma_f32_32x32x16_bf16 v[50:65], v[158:161], v[216:219], v[50:65]
	ds_read_b64_tr_b16 v[216:217], v255 offset:0x2400
	ds_read_b64_tr_b16 v[218:219], v255 offset:0x2c00
	ds_read_b64_tr_b16 v[220:221], v255 offset:0x3400
	ds_read_b64_tr_b16 v[222:223], v255 offset:0x3c00
	s_waitcnt lgkmcnt(0)
	v_mfma_f32_32x32x16_bf16 v[50:65], v[162:165], v[228:231], v[50:65]
	v_mfma_f32_32x32x16_bf16 v[34:49], v[146:149], v[208:211], v[34:49]
	ds_read_b64_tr_b16 v[208:209], v255 offset:0x600
	ds_read_b64_tr_b16 v[210:211], v255 offset:0xe00
	v_mfma_f32_32x32x16_bf16 v[34:49], v[154:157], v[212:215], v[34:49]
	ds_read_b64_tr_b16 v[212:213], v255 offset:0x1600
	ds_read_b64_tr_b16 v[214:215], v255 offset:0x1e00
	v_mfma_f32_32x32x16_bf16 v[34:49], v[158:161], v[216:219], v[34:49]
	ds_read_b64_tr_b16 v[216:217], v255 offset:0x2600
	ds_read_b64_tr_b16 v[218:219], v255 offset:0x2e00
	ds_read_b64_tr_b16 v[228:229], v255 offset:0x3600
	ds_read_b64_tr_b16 v[230:231], v255 offset:0x3e00
	s_waitcnt lgkmcnt(0)
	v_mfma_f32_32x32x16_bf16 v[34:49], v[162:165], v[220:223], v[34:49]
	v_mfma_f32_32x32x16_bf16 v[18:33], v[146:149], v[208:211], v[18:33]
	v_mfma_f32_32x32x16_bf16 v[18:33], v[154:157], v[212:215], v[18:33]
	v_mfma_f32_32x32x16_bf16 v[18:33], v[158:161], v[216:219], v[18:33]
	v_mfma_f32_32x32x16_bf16 v[18:33], v[162:165], v[228:231], v[18:33]
.LBB0_705:
	s_or_b64 exec, exec, s[12:13]
	v_max_f32_e32 v146, v83, v83
	v_max_f32_e32 v147, v82, v82
	v_max_f32_e32 v146, v147, v146
	v_max3_f32 v146, v146, v84, v85
	v_max3_f32 v146, v146, v86, v87
	v_max3_f32 v146, v146, v88, v89
	v_max3_f32 v146, v146, v90, v91
	v_max3_f32 v146, v146, v92, v93
	v_max3_f32 v146, v146, v94, v95
	v_max3_f32 v146, v146, v96, v97
	v_max3_f32 v146, v146, v66, v67
	v_max3_f32 v146, v146, v68, v69
	v_max3_f32 v146, v146, v70, v71
	v_max3_f32 v146, v146, v72, v73
	v_max3_f32 v146, v146, v74, v75
	v_max3_f32 v146, v146, v76, v77
	v_max3_f32 v146, v146, v78, v79
	v_max3_f32 v146, v146, v80, v81
	v_mov_b32_e32 v147, v146
	s_nop 1
	v_permlane32_swap_b32_e32 v146, v147
	v_max_f32_e32 v147, v147, v147
	v_max_f32_e32 v146, v146, v146
	v_max_f32_e32 v146, v146, v147
	v_max_f32_e32 v148, v201, v201
	v_sub_f32_e32 v147, v146, v201
	v_max_f32_e32 v146, v148, v146
	v_sub_f32_e32 v148, v201, v146
	v_mul_f32_e32 v148, 0x3dd53b94, v148
	v_exp_f32_e32 v148, v148
	v_cmp_ge_f32_e32 vcc, s80, v147
	s_cmp_eq_u64 vcc, exec
	s_cselect_b64 s[12:13], -1, 0
	s_waitcnt vmcnt(0)
	v_cndmask_b32_e64 v204, v148, 1.0, s[12:13]
	v_cmp_gt_f32_e32 vcc, 1.0, v204
	s_waitcnt vmcnt(4)
	ds_write_b128 v253, v[130:133]
	s_waitcnt vmcnt(3)
	ds_write_b128 v254, v[134:137]
	s_waitcnt vmcnt(2)
	ds_write_b128 v191, v[138:141] offset:32768
	s_waitcnt vmcnt(1)
	ds_write_b128 v191, v[142:145] offset:45056
	s_waitcnt vmcnt(0)
	ds_write_b128 v192, v[150:153] offset:32768
	s_cbranch_vccz .LBB0_709
	s_and_saveexec_b64 s[18:19], s[8:9]
	ds_write_b32 v171, v204 offset:128
	s_or_b64 exec, exec, s[18:19]
	s_waitcnt lgkmcnt(0)
	v_add_u32_e32 v142, v167, v170
	ds_read_b128 v[130:133], v142 offset:224
	ds_read_b128 v[134:137], v142 offset:192
	ds_read_b128 v[138:141], v142 offset:160
	ds_read_b128 v[142:145], v142 offset:128
	s_waitcnt lgkmcnt(3)
	v_pk_mul_f32 v[14:15], v[14:15], v[130:131]
	s_waitcnt lgkmcnt(2)
	v_pk_mul_f32 v[10:11], v[10:11], v[134:135]
	s_waitcnt lgkmcnt(1)
	v_pk_mul_f32 v[6:7], v[6:7], v[138:139]
	v_pk_mul_f32 v[16:17], v[16:17], v[132:133]
	v_pk_mul_f32 v[12:13], v[12:13], v[136:137]
	v_pk_mul_f32 v[8:9], v[8:9], v[140:141]
	s_waitcnt lgkmcnt(0)
	v_pk_mul_f32 v[4:5], v[4:5], v[144:145]
	v_pk_mul_f32 v[2:3], v[2:3], v[142:143]
	v_pk_mul_f32 v[62:63], v[62:63], v[130:131]
	v_pk_mul_f32 v[58:59], v[58:59], v[134:135]
	v_pk_mul_f32 v[54:55], v[54:55], v[138:139]
	v_pk_mul_f32 v[64:65], v[64:65], v[132:133]
	v_pk_mul_f32 v[60:61], v[60:61], v[136:137]
	v_pk_mul_f32 v[56:57], v[56:57], v[140:141]
	v_pk_mul_f32 v[52:53], v[52:53], v[144:145]
	v_pk_mul_f32 v[50:51], v[50:51], v[142:143]
	v_pk_mul_f32 v[46:47], v[46:47], v[130:131]
	v_pk_mul_f32 v[42:43], v[42:43], v[134:135]
	v_pk_mul_f32 v[38:39], v[38:39], v[138:139]
	v_pk_mul_f32 v[48:49], v[48:49], v[132:133]
	v_pk_mul_f32 v[44:45], v[44:45], v[136:137]
	v_pk_mul_f32 v[40:41], v[40:41], v[140:141]
	v_pk_mul_f32 v[36:37], v[36:37], v[144:145]
	v_pk_mul_f32 v[34:35], v[34:35], v[142:143]
	v_pk_mul_f32 v[30:31], v[30:31], v[130:131]
	v_pk_mul_f32 v[26:27], v[26:27], v[134:135]
	v_pk_mul_f32 v[22:23], v[22:23], v[138:139]
	v_pk_mul_f32 v[32:33], v[32:33], v[132:133]
	v_pk_mul_f32 v[28:29], v[28:29], v[136:137]
	v_pk_mul_f32 v[24:25], v[24:25], v[140:141]
	v_pk_mul_f32 v[20:21], v[20:21], v[144:145]
	v_pk_mul_f32 v[18:19], v[18:19], v[142:143]
.LBB0_709:
	v_cndmask_b32_e64 v201, v146, v201, s[12:13]
	v_mul_f32_e32 v140, 0xbdd53b94, v201
	v_fmamk_f32 v82, v82, 0x3dd53b94, v140
	v_fmamk_f32 v83, v83, 0x3dd53b94, v140
	v_fmamk_f32 v84, v84, 0x3dd53b94, v140
	v_fmamk_f32 v85, v85, 0x3dd53b94, v140
	v_fmamk_f32 v86, v86, 0x3dd53b94, v140
	v_fmamk_f32 v87, v87, 0x3dd53b94, v140
	v_fmamk_f32 v88, v88, 0x3dd53b94, v140
	v_fmamk_f32 v89, v89, 0x3dd53b94, v140
	v_fmamk_f32 v90, v90, 0x3dd53b94, v140
	v_fmamk_f32 v91, v91, 0x3dd53b94, v140
	v_fmamk_f32 v92, v92, 0x3dd53b94, v140
	v_fmamk_f32 v93, v93, 0x3dd53b94, v140
	v_fmamk_f32 v94, v94, 0x3dd53b94, v140
	v_fmamk_f32 v95, v95, 0x3dd53b94, v140
	v_fmamk_f32 v96, v96, 0x3dd53b94, v140
	v_fmamk_f32 v97, v97, 0x3dd53b94, v140
	v_exp_f32_e32 v133, v82
	v_exp_f32_e32 v136, v83
	v_exp_f32_e32 v137, v84
	v_exp_f32_e32 v141, v85
	v_exp_f32_e32 v142, v86
	v_exp_f32_e32 v144, v87
	v_exp_f32_e32 v145, v88
	v_exp_f32_e32 v146, v89
	v_exp_f32_e32 v130, v90
	v_exp_f32_e32 v131, v91
	v_exp_f32_e32 v132, v92
	v_exp_f32_e32 v134, v93
	v_exp_f32_e32 v135, v94
	v_exp_f32_e32 v138, v95
	v_exp_f32_e32 v139, v96
	v_exp_f32_e32 v143, v97
	v_fmamk_f32 v147, v66, 0x3dd53b94, v140
	v_fmamk_f32 v148, v67, 0x3dd53b94, v140
	v_fmamk_f32 v149, v68, 0x3dd53b94, v140
	v_fmamk_f32 v150, v69, 0x3dd53b94, v140
	v_fmamk_f32 v151, v70, 0x3dd53b94, v140
	v_fmamk_f32 v152, v71, 0x3dd53b94, v140
	v_fmamk_f32 v153, v72, 0x3dd53b94, v140
	v_fmamk_f32 v154, v73, 0x3dd53b94, v140
	v_fmamk_f32 v155, v74, 0x3dd53b94, v140
	v_fmamk_f32 v156, v75, 0x3dd53b94, v140
	v_fmamk_f32 v157, v76, 0x3dd53b94, v140
	v_fmamk_f32 v158, v77, 0x3dd53b94, v140
	v_fmamk_f32 v159, v78, 0x3dd53b94, v140
	v_fmamk_f32 v160, v79, 0x3dd53b94, v140
	v_fmamk_f32 v161, v80, 0x3dd53b94, v140
	v_fmac_f32_e32 v140, 0x3dd53b94, v81
	s_waitcnt lgkmcnt(0)
	s_barrier
	s_mov_b32 s98, s99
	s_cmp_eq_u32 s98, 0x4000
	s_cselect_b32 s99, 0x1d800, 0
	s_cmp_eq_u32 s98, 0
	s_cselect_b32 s99, 0x4000, s99
	s_cmp_eq_u32 s99, 0x4000
	s_cselect_b32 s100, 0x1d800, 0
	s_cmp_eq_u32 s99, 0
	s_cselect_b32 s100, 0x4000, s100
	v_add_u32_e32 v255, s98, v182
	v_add_u32_e32 v253, s100, v189
	v_add_u32_e32 v254, s100, v190
	v_cmp_lt_i32_e32 vcc, s17, v193
	v_mov_b32_e32 v66, 0xf149f2ca
	v_mov_b32_e32 v67, 0xf149f2ca
	v_mov_b32_e32 v68, 0xf149f2ca
	v_mov_b32_e32 v69, 0xf149f2ca
	v_mov_b32_e32 v70, 0xf149f2ca
	v_mov_b32_e32 v71, 0xf149f2ca
	v_mov_b32_e32 v72, 0xf149f2ca
	v_mov_b32_e32 v73, 0xf149f2ca
	v_mov_b32_e32 v74, 0xf149f2ca
	v_mov_b32_e32 v75, 0xf149f2ca
	v_mov_b32_e32 v76, 0xf149f2ca
	v_mov_b32_e32 v77, 0xf149f2ca
	v_mov_b32_e32 v78, 0xf149f2ca
	v_mov_b32_e32 v79, 0xf149f2ca
	v_mov_b32_e32 v80, 0xf149f2ca
	v_mov_b32_e32 v81, 0xf149f2ca
	v_mov_b32_e32 v82, 0xf149f2ca
	v_mov_b32_e32 v83, 0xf149f2ca
	v_mov_b32_e32 v84, 0xf149f2ca
	v_mov_b32_e32 v85, 0xf149f2ca
	v_mov_b32_e32 v86, 0xf149f2ca
	v_mov_b32_e32 v87, 0xf149f2ca
	v_mov_b32_e32 v88, 0xf149f2ca
	v_mov_b32_e32 v89, 0xf149f2ca
	v_mov_b32_e32 v90, 0xf149f2ca
	v_mov_b32_e32 v91, 0xf149f2ca
	v_mov_b32_e32 v92, 0xf149f2ca
	v_mov_b32_e32 v93, 0xf149f2ca
	v_mov_b32_e32 v94, 0xf149f2ca
	v_mov_b32_e32 v95, 0xf149f2ca
	v_mov_b32_e32 v96, 0xf149f2ca
	v_mov_b32_e32 v97, 0xf149f2ca
	s_and_saveexec_b64 s[12:13], vcc
	s_cbranch_execz .LBB0_711
	ds_read_b128 v[162:165], v185 offset:32768
	ds_read_b128 v[208:211], v185 offset:45056
	ds_read_b128 v[212:215], v186 offset:32768
	ds_read_b128 v[216:219], v186 offset:45056
	ds_read_b128 v[220:223], v188 offset:32768
	ds_read_b128 v[228:231], v188 offset:45056
	s_waitcnt lgkmcnt(5)
	v_mfma_f32_32x32x16_bf16 v[66:81], v[162:165], v[126:129], 0
	ds_read_b128 v[232:235], v187 offset:32768
	s_waitcnt lgkmcnt(5)
	v_mfma_f32_32x32x16_bf16 v[82:97], v[208:211], v[126:129], 0
	ds_read_b128 v[162:165], v187 offset:45056
	s_waitcnt lgkmcnt(5)
	v_mfma_f32_32x32x16_bf16 v[66:81], v[212:215], v[122:125], v[66:81]
	ds_read_b128 v[208:211], v185 offset:32896
	s_waitcnt lgkmcnt(5)
	v_mfma_f32_32x32x16_bf16 v[82:97], v[216:219], v[122:125], v[82:97]
	ds_read_b128 v[212:215], v185 offset:45184
	s_waitcnt lgkmcnt(5)
	v_mfma_f32_32x32x16_bf16 v[66:81], v[220:223], v[118:121], v[66:81]
	ds_read_b128 v[216:219], v186 offset:32896
	s_waitcnt lgkmcnt(5)
	v_mfma_f32_32x32x16_bf16 v[82:97], v[228:231], v[118:121], v[82:97]
	ds_read_b128 v[220:223], v186 offset:45184
	s_waitcnt lgkmcnt(5)
	v_mfma_f32_32x32x16_bf16 v[66:81], v[232:235], v[114:117], v[66:81]
	ds_read_b128 v[228:231], v188 offset:32896
	s_waitcnt lgkmcnt(5)
	v_mfma_f32_32x32x16_bf16 v[82:97], v[162:165], v[114:117], v[82:97]
	ds_read_b128 v[232:235], v188 offset:45184
	ds_read_b128 v[236:239], v183
	s_waitcnt lgkmcnt(6)
	v_mfma_f32_32x32x16_bf16 v[66:81], v[208:211], v[110:113], v[66:81]
	ds_read_b128 v[162:165], v187 offset:32896
	s_waitcnt lgkmcnt(6)
	v_mfma_f32_32x32x16_bf16 v[82:97], v[212:215], v[110:113], v[82:97]
	ds_read_b128 v[208:211], v187 offset:45184
	ds_read_b128 v[240:243], v183 offset:32
	s_waitcnt lgkmcnt(7)
	v_mfma_f32_32x32x16_bf16 v[66:81], v[216:219], v[106:109], v[66:81]
	ds_read_b128 v[212:215], v185 offset:33024
	s_waitcnt lgkmcnt(7)
	v_mfma_f32_32x32x16_bf16 v[82:97], v[220:223], v[106:109], v[82:97]
	ds_read_b128 v[216:219], v185 offset:45312
	ds_read_b128 v[244:247], v183 offset:64
	s_waitcnt lgkmcnt(8)
	v_mfma_f32_32x32x16_bf16 v[66:81], v[228:231], v[102:105], v[66:81]
	ds_read_b128 v[220:223], v186 offset:33024
	s_waitcnt lgkmcnt(8)
	v_mfma_f32_32x32x16_bf16 v[82:97], v[232:235], v[102:105], v[82:97]
	ds_read_b128 v[228:231], v186 offset:45312
	s_waitcnt lgkmcnt(7)
	v_mfma_f32_32x32x16_bf16 v[66:81], v[162:165], v[98:101], v[66:81]
	ds_read_b128 v[232:235], v188 offset:33024
	s_waitcnt lgkmcnt(7)
	v_mfma_f32_32x32x16_bf16 v[82:97], v[208:211], v[98:101], v[82:97]
	ds_read_b128 v[162:165], v188 offset:45312
	s_waitcnt lgkmcnt(6)
	v_mfma_f32_32x32x16_bf16 v[66:81], v[212:215], v[236:239], v[66:81]
	ds_read_b128 v[208:211], v187 offset:33024
	s_waitcnt lgkmcnt(6)
	v_mfma_f32_32x32x16_bf16 v[82:97], v[216:219], v[236:239], v[82:97]
	ds_read_b128 v[212:215], v187 offset:45312
	ds_read_b128 v[236:239], v183 offset:96
	s_waitcnt lgkmcnt(6)
	v_mfma_f32_32x32x16_bf16 v[66:81], v[220:223], v[240:243], v[66:81]
	s_waitcnt lgkmcnt(5)
	v_mfma_f32_32x32x16_bf16 v[82:97], v[228:231], v[240:243], v[82:97]
	s_waitcnt lgkmcnt(4)
	v_mfma_f32_32x32x16_bf16 v[66:81], v[232:235], v[244:247], v[66:81]
	s_waitcnt lgkmcnt(3)
	v_mfma_f32_32x32x16_bf16 v[82:97], v[162:165], v[244:247], v[82:97]
	s_waitcnt lgkmcnt(0)
	v_mfma_f32_32x32x16_bf16 v[66:81], v[208:211], v[236:239], v[66:81]
	s_waitcnt lgkmcnt(0)
	v_mfma_f32_32x32x16_bf16 v[82:97], v[212:215], v[236:239], v[82:97]
.LBB0_711:
	s_or_b64 exec, exec, s[12:13]
	v_exp_f32_e32 v162, v150
	v_add_f32_e32 v150, 0, v133
	v_add_f32_e32 v150, v136, v150
	v_add_f32_e32 v150, v137, v150
	v_add_f32_e32 v150, v141, v150
	v_add_f32_e32 v150, v142, v150
	v_add_f32_e32 v150, v144, v150
	v_add_f32_e32 v150, v145, v150
	v_add_f32_e32 v150, v146, v150
	v_add_f32_e32 v150, v130, v150
	v_add_f32_e32 v150, v131, v150
	v_add_f32_e32 v150, v132, v150
	v_add_f32_e32 v150, v134, v150
	v_exp_f32_e32 v147, v147
	v_add_f32_e32 v150, v135, v150
	v_exp_f32_e32 v148, v148
	v_add_f32_e32 v150, v138, v150
	v_exp_f32_e32 v149, v149
	v_add_f32_e32 v150, v139, v150
	v_add_f32_e32 v150, v143, v150
	v_exp_f32_e32 v163, v151
	v_add_f32_e32 v150, v147, v150
	v_exp_f32_e32 v164, v152
	v_add_f32_e32 v150, v148, v150
	v_exp_f32_e32 v165, v153
	v_add_f32_e32 v150, v149, v150
	v_exp_f32_e32 v210, v154
	v_add_f32_e32 v150, v162, v150
	v_exp_f32_e32 v211, v155
	v_add_f32_e32 v150, v163, v150
	v_exp_f32_e32 v212, v156
	v_add_f32_e32 v150, v164, v150
	v_exp_f32_e32 v213, v157
	v_add_f32_e32 v150, v165, v150
	v_exp_f32_e32 v214, v158
	v_add_f32_e32 v150, v210, v150
	v_exp_f32_e32 v215, v159
	v_add_f32_e32 v150, v211, v150
	v_exp_f32_e32 v216, v160
	v_add_f32_e32 v150, v212, v150
	v_exp_f32_e32 v217, v161
	v_add_f32_e32 v150, v213, v150
	v_exp_f32_e32 v140, v140
	v_add_f32_e32 v150, v214, v150
	v_add_f32_e32 v150, v215, v150
	v_add_f32_e32 v150, v216, v150
	v_add_f32_e32 v150, v217, v150
	v_add_f32_e32 v208, v140, v150
	v_mov_b32_e32 v209, v208
	v_cvt_pk_bf16_f32 v150, v133, v136
	v_cvt_pk_bf16_f32 v151, v137, v141
	v_cvt_pk_bf16_f32 v152, v142, v144
	v_cvt_pk_bf16_f32 v153, v145, v146
	v_cvt_pk_bf16_f32 v154, v130, v131
	v_cvt_pk_bf16_f32 v155, v132, v134
	v_cvt_pk_bf16_f32 v156, v135, v138
	v_cvt_pk_bf16_f32 v157, v139, v143
	v_cvt_pk_bf16_f32 v158, v147, v148
	v_cvt_pk_bf16_f32 v159, v149, v162
	v_cvt_pk_bf16_f32 v160, v163, v164
	v_cvt_pk_bf16_f32 v161, v165, v210
	v_cvt_pk_bf16_f32 v162, v211, v212
	v_cvt_pk_bf16_f32 v163, v213, v214
	v_cvt_pk_bf16_f32 v164, v215, v216
	v_cvt_pk_bf16_f32 v165, v217, v140
	v_permlane32_swap_b32_e32 v208, v209
	v_permlane32_swap_b32_e32 v150, v152
	v_permlane32_swap_b32_e32 v151, v153
	v_permlane32_swap_b32_e32 v154, v156
	v_permlane32_swap_b32_e32 v155, v157
	v_permlane32_swap_b32_e32 v158, v160
	v_permlane32_swap_b32_e32 v159, v161
	v_permlane32_swap_b32_e32 v162, v164
	v_permlane32_swap_b32_e32 v163, v165
	v_add_u32_e32 v130, 0xc0, v205
	v_add_u32_e32 v132, 0xe0, v205
	v_ashrrev_i32_e32 v131, 31, v130
	v_ashrrev_i32_e32 v133, 31, v132
	v_add_u32_e32 v146, 0xc0, v207
	v_lshlrev_b64 v[138:139], 11, v[130:131]
	v_lshlrev_b64 v[140:141], 11, v[132:133]
	v_ashrrev_i32_e32 v147, 31, v146
	v_or_b32_e32 v138, v138, v206
	v_or_b32_e32 v140, v140, v206
	v_lshlrev_b64 v[146:147], 7, v[146:147]
	v_lshl_add_u64 v[130:131], s[14:15], 0, v[138:139]
	v_lshl_add_u64 v[134:135], s[14:15], 0, v[140:141]
	v_lshl_add_u64 v[138:139], s[64:65], 0, v[138:139]
	v_lshl_add_u64 v[142:143], s[64:65], 0, v[140:141]
	v_lshl_add_u64 v[146:147], v[178:179], 0, v[146:147]
	global_load_dwordx4 v[130:133], v[130:131], off
	s_nop 0
	global_load_dwordx4 v[134:137], v[134:135], off
	s_nop 0
	global_load_dwordx4 v[138:141], v[138:139], off
	s_nop 0
	global_load_dwordx4 v[142:145], v[142:143], off
	s_nop 0
	global_load_dwordx4 v[146:149], v[146:147], off
	s_and_saveexec_b64 s[12:13], s[10:11]
	s_cbranch_execz .LBB0_713
	ds_read_b64_tr_b16 v[210:211], v255 offset:0
	ds_read_b64_tr_b16 v[212:213], v255 offset:0x800
	ds_read_b64_tr_b16 v[214:215], v255 offset:0x1000
	ds_read_b64_tr_b16 v[216:217], v255 offset:0x1800
	ds_read_b64_tr_b16 v[218:219], v255 offset:0x2000
	ds_read_b64_tr_b16 v[220:221], v255 offset:0x2800
	ds_read_b64_tr_b16 v[222:223], v255 offset:0x3000
	ds_read_b64_tr_b16 v[224:225], v255 offset:0x3800
	s_waitcnt lgkmcnt(0)
	s_nop 0
	v_mfma_f32_32x32x16_bf16 v[2:17], v[150:153], v[210:213], v[2:17]
	ds_read_b64_tr_b16 v[210:211], v255 offset:0x200
	ds_read_b64_tr_b16 v[212:213], v255 offset:0xa00
	v_mfma_f32_32x32x16_bf16 v[2:17], v[154:157], v[214:217], v[2:17]
	ds_read_b64_tr_b16 v[214:215], v255 offset:0x1200
	ds_read_b64_tr_b16 v[216:217], v255 offset:0x1a00
	v_mfma_f32_32x32x16_bf16 v[2:17], v[158:161], v[218:221], v[2:17]
	ds_read_b64_tr_b16 v[218:219], v255 offset:0x2200
	ds_read_b64_tr_b16 v[220:221], v255 offset:0x2a00
	ds_read_b64_tr_b16 v[228:229], v255 offset:0x3200
	ds_read_b64_tr_b16 v[230:231], v255 offset:0x3a00
	s_waitcnt lgkmcnt(0)
	v_mfma_f32_32x32x16_bf16 v[2:17], v[162:165], v[222:225], v[2:17]
	v_mfma_f32_32x32x16_bf16 v[50:65], v[150:153], v[210:213], v[50:65]
	ds_read_b64_tr_b16 v[210:211], v255 offset:0x400
	ds_read_b64_tr_b16 v[212:213], v255 offset:0xc00
	v_mfma_f32_32x32x16_bf16 v[50:65], v[154:157], v[214:217], v[50:65]
	ds_read_b64_tr_b16 v[214:215], v255 offset:0x1400
	ds_read_b64_tr_b16 v[216:217], v255 offset:0x1c00
	v_mfma_f32_32x32x16_bf16 v[50:65], v[158:161], v[218:221], v[50:65]
	ds_read_b64_tr_b16 v[218:219], v255 offset:0x2400
	ds_read_b64_tr_b16 v[220:221], v255 offset:0x2c00
	ds_read_b64_tr_b16 v[222:223], v255 offset:0x3400
	ds_read_b64_tr_b16 v[224:225], v255 offset:0x3c00
	s_waitcnt lgkmcnt(0)
	v_mfma_f32_32x32x16_bf16 v[50:65], v[162:165], v[228:231], v[50:65]
	v_mfma_f32_32x32x16_bf16 v[34:49], v[150:153], v[210:213], v[34:49]
	ds_read_b64_tr_b16 v[210:211], v255 offset:0x600
	ds_read_b64_tr_b16 v[212:213], v255 offset:0xe00
	v_mfma_f32_32x32x16_bf16 v[34:49], v[154:157], v[214:217], v[34:49]
	ds_read_b64_tr_b16 v[214:215], v255 offset:0x1600
	ds_read_b64_tr_b16 v[216:217], v255 offset:0x1e00
	v_mfma_f32_32x32x16_bf16 v[34:49], v[158:161], v[218:221], v[34:49]
	ds_read_b64_tr_b16 v[218:219], v255 offset:0x2600
	ds_read_b64_tr_b16 v[220:221], v255 offset:0x2e00
	ds_read_b64_tr_b16 v[228:229], v255 offset:0x3600
	ds_read_b64_tr_b16 v[230:231], v255 offset:0x3e00
	s_waitcnt lgkmcnt(0)
	v_mfma_f32_32x32x16_bf16 v[34:49], v[162:165], v[222:225], v[34:49]
	v_mfma_f32_32x32x16_bf16 v[18:33], v[150:153], v[210:213], v[18:33]
	v_mfma_f32_32x32x16_bf16 v[18:33], v[154:157], v[214:217], v[18:33]
	v_mfma_f32_32x32x16_bf16 v[18:33], v[158:161], v[218:221], v[18:33]
	v_mfma_f32_32x32x16_bf16 v[18:33], v[162:165], v[228:231], v[18:33]
.LBB0_713:
	s_or_b64 exec, exec, s[12:13]
	v_max_f32_e32 v150, v67, v67
	v_max_f32_e32 v151, v66, v66
	v_max_f32_e32 v150, v151, v150
	v_max3_f32 v150, v150, v68, v69
	v_max3_f32 v150, v150, v70, v71
	v_max3_f32 v150, v150, v72, v73
	v_max3_f32 v150, v150, v74, v75
	v_max3_f32 v150, v150, v76, v77
	v_max3_f32 v150, v150, v78, v79
	v_max3_f32 v150, v150, v80, v81
	v_max3_f32 v150, v150, v82, v83
	v_max3_f32 v150, v150, v84, v85
	v_max3_f32 v150, v150, v86, v87
	v_max3_f32 v150, v150, v88, v89
	v_max3_f32 v150, v150, v90, v91
	v_max3_f32 v150, v150, v92, v93
	v_max3_f32 v150, v150, v94, v95
	v_max3_f32 v150, v150, v96, v97
	v_mov_b32_e32 v151, v150
	s_nop 1
	v_permlane32_swap_b32_e32 v150, v151
	v_max_f32_e32 v151, v151, v151
	v_max_f32_e32 v150, v150, v150
	v_max_f32_e32 v150, v150, v151
	v_max_f32_e32 v151, v201, v201
	v_max_f32_e32 v151, v151, v150
	v_sub_f32_e32 v152, v150, v201
	v_sub_f32_e32 v150, v201, v151
	v_mul_f32_e32 v150, 0x3dd53b94, v150
	v_exp_f32_e32 v150, v150
	v_cmp_ge_f32_e32 vcc, s80, v152
	s_cmp_eq_u64 vcc, exec
	s_cselect_b64 s[10:11], -1, 0
	s_waitcnt vmcnt(0)
	v_cndmask_b32_e64 v150, v150, 1.0, s[10:11]
	v_cmp_gt_f32_e32 vcc, 1.0, v150
	s_waitcnt vmcnt(4)
	ds_write_b128 v253, v[130:133]
	s_waitcnt vmcnt(3)
	ds_write_b128 v254, v[134:137]
	s_waitcnt vmcnt(2)
	ds_write_b128 v191, v[138:141] offset:57344
	s_waitcnt vmcnt(1)
	ds_write_b128 v194, v[142:145] offset:57344
	s_waitcnt vmcnt(0)
	ds_write_b128 v192, v[146:149] offset:57344
	s_cbranch_vccz .LBB0_717
	s_and_saveexec_b64 s[12:13], s[8:9]
	ds_write_b32 v171, v150 offset:128
	s_or_b64 exec, exec, s[12:13]
	s_waitcnt lgkmcnt(0)
	v_add_u32_e32 v142, v167, v170
	ds_read_b128 v[130:133], v142 offset:224
	ds_read_b128 v[134:137], v142 offset:192
	ds_read_b128 v[138:141], v142 offset:160
	ds_read_b128 v[142:145], v142 offset:128
	s_waitcnt lgkmcnt(3)
	v_pk_mul_f32 v[14:15], v[14:15], v[130:131]
	s_waitcnt lgkmcnt(2)
	v_pk_mul_f32 v[10:11], v[10:11], v[134:135]
	s_waitcnt lgkmcnt(1)
	v_pk_mul_f32 v[6:7], v[6:7], v[138:139]
	v_pk_mul_f32 v[16:17], v[16:17], v[132:133]
	v_pk_mul_f32 v[12:13], v[12:13], v[136:137]
	v_pk_mul_f32 v[8:9], v[8:9], v[140:141]
	s_waitcnt lgkmcnt(0)
	v_pk_mul_f32 v[4:5], v[4:5], v[144:145]
	v_pk_mul_f32 v[2:3], v[2:3], v[142:143]
	v_pk_mul_f32 v[62:63], v[62:63], v[130:131]
	v_pk_mul_f32 v[58:59], v[58:59], v[134:135]
	v_pk_mul_f32 v[54:55], v[54:55], v[138:139]
	v_pk_mul_f32 v[64:65], v[64:65], v[132:133]
	v_pk_mul_f32 v[60:61], v[60:61], v[136:137]
	v_pk_mul_f32 v[56:57], v[56:57], v[140:141]
	v_pk_mul_f32 v[52:53], v[52:53], v[144:145]
	v_pk_mul_f32 v[50:51], v[50:51], v[142:143]
	v_pk_mul_f32 v[46:47], v[46:47], v[130:131]
	v_pk_mul_f32 v[42:43], v[42:43], v[134:135]
	v_pk_mul_f32 v[38:39], v[38:39], v[138:139]
	v_pk_mul_f32 v[48:49], v[48:49], v[132:133]
	v_pk_mul_f32 v[44:45], v[44:45], v[136:137]
	v_pk_mul_f32 v[40:41], v[40:41], v[140:141]
	v_pk_mul_f32 v[36:37], v[36:37], v[144:145]
	v_pk_mul_f32 v[34:35], v[34:35], v[142:143]
	v_pk_mul_f32 v[30:31], v[30:31], v[130:131]
	v_pk_mul_f32 v[26:27], v[26:27], v[134:135]
	v_pk_mul_f32 v[22:23], v[22:23], v[138:139]
	v_pk_mul_f32 v[32:33], v[32:33], v[132:133]
	v_pk_mul_f32 v[28:29], v[28:29], v[136:137]
	v_pk_mul_f32 v[24:25], v[24:25], v[140:141]
	v_pk_mul_f32 v[20:21], v[20:21], v[144:145]
	v_pk_mul_f32 v[18:19], v[18:19], v[142:143]
.LBB0_717:
	v_cndmask_b32_e64 v201, v151, v201, s[10:11]
	v_mul_f32_e32 v140, 0xbdd53b94, v201
	v_mov_b32_e32 v141, v140
	v_fmamk_f32 v66, v66, 0x3dd53b94, v140
	v_fmamk_f32 v67, v67, 0x3dd53b94, v140
	v_fmamk_f32 v68, v68, 0x3dd53b94, v140
	v_fmamk_f32 v69, v69, 0x3dd53b94, v140
	v_fmamk_f32 v70, v70, 0x3dd53b94, v140
	v_fmamk_f32 v71, v71, 0x3dd53b94, v140
	v_fmamk_f32 v72, v72, 0x3dd53b94, v140
	v_fmamk_f32 v73, v73, 0x3dd53b94, v140
	v_fmamk_f32 v74, v74, 0x3dd53b94, v140
	v_fmamk_f32 v75, v75, 0x3dd53b94, v140
	v_fmamk_f32 v76, v76, 0x3dd53b94, v140
	v_fmamk_f32 v77, v77, 0x3dd53b94, v140
	v_fmamk_f32 v78, v78, 0x3dd53b94, v140
	v_fmamk_f32 v79, v79, 0x3dd53b94, v140
	v_fmamk_f32 v80, v80, 0x3dd53b94, v140
	v_fmac_f32_e32 v141, 0x3dd53b94, v81
	v_exp_f32_e32 v146, v66
	v_exp_f32_e32 v147, v67
	v_exp_f32_e32 v148, v68
	v_exp_f32_e32 v149, v69
	v_exp_f32_e32 v154, v70
	v_exp_f32_e32 v160, v71
	v_exp_f32_e32 v161, v72
	v_exp_f32_e32 v162, v73
	v_exp_f32_e32 v151, v74
	v_exp_f32_e32 v152, v75
	v_exp_f32_e32 v153, v76
	v_exp_f32_e32 v155, v77
	v_exp_f32_e32 v156, v78
	v_exp_f32_e32 v157, v79
	v_exp_f32_e32 v158, v80
	v_exp_f32_e32 v159, v141
	v_add_f32_e32 v66, v202, v203
	v_fmac_f32_e32 v66, v199, v173
	v_add_f32_e32 v173, v208, v209
	s_addk_i32 s16, 0x80
	s_add_i32 s91, s91, 2
	v_pk_fma_f32 v[138:139], v[82:83], s[62:63], v[140:141] op_sel_hi:[1,0,0]
	v_pk_fma_f32 v[136:137], v[84:85], s[62:63], v[140:141] op_sel_hi:[1,0,0]
	v_pk_fma_f32 v[134:135], v[86:87], s[62:63], v[140:141] op_sel_hi:[1,0,0]
	v_pk_fma_f32 v[132:133], v[88:89], s[62:63], v[140:141] op_sel_hi:[1,0,0]
	v_pk_fma_f32 v[130:131], v[90:91], s[62:63], v[140:141] op_sel_hi:[1,0,0]
	v_pk_fma_f32 v[144:145], v[92:93], s[62:63], v[140:141] op_sel_hi:[1,0,0]
	v_pk_fma_f32 v[142:143], v[94:95], s[62:63], v[140:141] op_sel_hi:[1,0,0]
	v_pk_fma_f32 v[140:141], v[96:97], s[62:63], v[140:141] op_sel_hi:[1,0,0]
	v_fmac_f32_e32 v173, v66, v204
	s_mov_b32 s98, s99
	s_cmp_ge_u32 s91, s92
	s_waitcnt lgkmcnt(0)
	s_barrier
	s_cbranch_scc1 .LBB0_719
	v_mov_b32_e32 v199, v150
	s_branch .LBB0_701
.LBB0_719:
	s_cmp_eq_u32 s98, 0x4000
	s_cselect_b32 s99, 0x1d800, 0
	s_cmp_eq_u32 s98, 0
	s_cselect_b32 s99, 0x4000, s99
	v_add_u32_e32 v255, s98, v182
	v_add_u32_e32 v254, s99, v182
	v_cmp_lt_i32_e64 s[10:11], 2, v184
	v_mov_b32_e32 v66, 0xf149f2ca
	v_mov_b32_e32 v67, 0xf149f2ca
	v_mov_b32_e32 v68, 0xf149f2ca
	v_mov_b32_e32 v69, 0xf149f2ca
	v_mov_b32_e32 v70, 0xf149f2ca
	v_mov_b32_e32 v71, 0xf149f2ca
	v_mov_b32_e32 v72, 0xf149f2ca
	v_mov_b32_e32 v73, 0xf149f2ca
	v_mov_b32_e32 v74, 0xf149f2ca
	v_mov_b32_e32 v75, 0xf149f2ca
	v_mov_b32_e32 v76, 0xf149f2ca
	v_mov_b32_e32 v77, 0xf149f2ca
	v_mov_b32_e32 v78, 0xf149f2ca
	v_mov_b32_e32 v79, 0xf149f2ca
	v_mov_b32_e32 v80, 0xf149f2ca
	v_mov_b32_e32 v81, 0xf149f2ca
	v_mov_b32_e32 v82, 0xf149f2ca
	v_mov_b32_e32 v83, 0xf149f2ca
	v_mov_b32_e32 v84, 0xf149f2ca
	v_mov_b32_e32 v85, 0xf149f2ca
	v_mov_b32_e32 v86, 0xf149f2ca
	v_mov_b32_e32 v87, 0xf149f2ca
	v_mov_b32_e32 v88, 0xf149f2ca
	v_mov_b32_e32 v89, 0xf149f2ca
	v_mov_b32_e32 v90, 0xf149f2ca
	v_mov_b32_e32 v91, 0xf149f2ca
	v_mov_b32_e32 v92, 0xf149f2ca
	v_mov_b32_e32 v93, 0xf149f2ca
	v_mov_b32_e32 v94, 0xf149f2ca
	v_mov_b32_e32 v95, 0xf149f2ca
	v_mov_b32_e32 v96, 0xf149f2ca
	v_mov_b32_e32 v97, 0xf149f2ca
	s_and_saveexec_b64 s[12:13], s[10:11]
	s_cbranch_execz .LBB0_721
	ds_read_b128 v[66:69], v185 offset:57344
	ds_read_b128 v[190:193], v185 offset:57472
	s_waitcnt lgkmcnt(1)
	v_mfma_f32_32x32x16_bf16 v[82:97], v[66:69], v[126:129], 0
	ds_read_b128 v[66:69], v198 offset:12288
	ds_read_b128 v[202:205], v198 offset:12416
	s_waitcnt lgkmcnt(1)
	v_mfma_f32_32x32x16_bf16 v[66:81], v[66:69], v[126:129], 0
	ds_read_b128 v[126:129], v186 offset:57344
	ds_read_b128 v[206:209], v185 offset:57600
	s_waitcnt lgkmcnt(1)
	v_mfma_f32_32x32x16_bf16 v[82:97], v[126:129], v[122:125], v[82:97]
	ds_read_b128 v[126:129], v196 offset:12288
	ds_read_b128 v[210:213], v198 offset:12544
	s_waitcnt lgkmcnt(1)
	v_mfma_f32_32x32x16_bf16 v[66:81], v[126:129], v[122:125], v[66:81]
	ds_read_b128 v[122:125], v188 offset:57344
	ds_read_b128 v[126:129], v188 offset:57472
	s_waitcnt lgkmcnt(1)
	v_mfma_f32_32x32x16_bf16 v[82:97], v[122:125], v[118:121], v[82:97]
	ds_read_b128 v[122:125], v197 offset:12288
	ds_read_b128 v[214:217], v197 offset:12416
	s_waitcnt lgkmcnt(1)
	v_mfma_f32_32x32x16_bf16 v[66:81], v[122:125], v[118:121], v[66:81]
	ds_read_b128 v[118:121], v187 offset:57344
	ds_read_b128 v[122:125], v188 offset:57600
	s_waitcnt lgkmcnt(1)
	v_mfma_f32_32x32x16_bf16 v[82:97], v[118:121], v[114:117], v[82:97]
	ds_read_b128 v[118:121], v195 offset:12288
	ds_read_b128 v[218:221], v197 offset:12544
	s_waitcnt lgkmcnt(1)
	v_mfma_f32_32x32x16_bf16 v[66:81], v[118:121], v[114:117], v[66:81]
	v_mfma_f32_32x32x16_bf16 v[82:97], v[190:193], v[110:113], v[82:97]
	v_mfma_f32_32x32x16_bf16 v[66:81], v[202:205], v[110:113], v[66:81]
	ds_read_b128 v[110:113], v186 offset:57472
	ds_read_b128 v[114:117], v186 offset:57600
	s_waitcnt lgkmcnt(1)
	v_mfma_f32_32x32x16_bf16 v[82:97], v[110:113], v[106:109], v[82:97]
	ds_read_b128 v[110:113], v196 offset:12416
	ds_read_b128 v[118:121], v196 offset:12544
	s_waitcnt lgkmcnt(1)
	v_mfma_f32_32x32x16_bf16 v[66:81], v[110:113], v[106:109], v[66:81]
	v_mfma_f32_32x32x16_bf16 v[82:97], v[126:129], v[102:105], v[82:97]
	v_mfma_f32_32x32x16_bf16 v[66:81], v[214:217], v[102:105], v[66:81]
	ds_read_b128 v[102:105], v187 offset:57472
	ds_read_b128 v[106:109], v187 offset:57600
	s_waitcnt lgkmcnt(1)
	v_mfma_f32_32x32x16_bf16 v[82:97], v[102:105], v[98:101], v[82:97]
	ds_read_b128 v[102:105], v195 offset:12416
	ds_read_b128 v[110:113], v195 offset:12544
	s_waitcnt lgkmcnt(1)
	v_mfma_f32_32x32x16_bf16 v[66:81], v[102:105], v[98:101], v[66:81]
	ds_read_b128 v[98:101], v183
	ds_read_b128 v[102:105], v183 offset:32
	s_waitcnt lgkmcnt(1)
	v_mfma_f32_32x32x16_bf16 v[82:97], v[206:209], v[98:101], v[82:97]
	v_mfma_f32_32x32x16_bf16 v[66:81], v[210:213], v[98:101], v[66:81]
	s_waitcnt lgkmcnt(0)
	v_mfma_f32_32x32x16_bf16 v[82:97], v[114:117], v[102:105], v[82:97]
	v_mfma_f32_32x32x16_bf16 v[66:81], v[118:121], v[102:105], v[66:81]
	ds_read_b128 v[98:101], v183 offset:64
	ds_read_b128 v[102:105], v183 offset:96
	s_waitcnt lgkmcnt(1)
	v_mfma_f32_32x32x16_bf16 v[82:97], v[122:125], v[98:101], v[82:97]
	v_mfma_f32_32x32x16_bf16 v[66:81], v[218:221], v[98:101], v[66:81]
	s_waitcnt lgkmcnt(0)
	v_mfma_f32_32x32x16_bf16 v[82:97], v[106:109], v[102:105], v[82:97]
	v_mfma_f32_32x32x16_bf16 v[66:81], v[110:113], v[102:105], v[66:81]
.LBB0_721:
	s_or_b64 exec, exec, s[12:13]
	v_add_f32_e32 v98, 0, v146
	v_add_f32_e32 v98, v147, v98
	v_add_f32_e32 v98, v148, v98
	v_add_f32_e32 v98, v149, v98
	v_add_f32_e32 v98, v154, v98
	v_add_f32_e32 v98, v160, v98
	v_add_f32_e32 v98, v161, v98
	v_add_f32_e32 v98, v162, v98
	v_add_f32_e32 v98, v151, v98
	v_add_f32_e32 v98, v152, v98
	v_add_f32_e32 v98, v153, v98
	v_add_f32_e32 v98, v155, v98
	v_exp_f32_e32 v106, v138
	v_add_f32_e32 v98, v156, v98
	v_exp_f32_e32 v107, v139
	v_add_f32_e32 v98, v157, v98
	v_exp_f32_e32 v108, v136
	v_add_f32_e32 v98, v158, v98
	v_exp_f32_e32 v109, v137
	v_add_f32_e32 v98, v159, v98
	v_exp_f32_e32 v110, v134
	v_add_f32_e32 v98, v106, v98
	v_exp_f32_e32 v111, v135
	v_add_f32_e32 v98, v107, v98
	v_exp_f32_e32 v112, v132
	v_add_f32_e32 v98, v108, v98
	v_exp_f32_e32 v113, v133
	v_add_f32_e32 v98, v109, v98
	v_exp_f32_e32 v116, v130
	v_add_f32_e32 v98, v110, v98
	v_exp_f32_e32 v117, v131
	v_add_f32_e32 v98, v111, v98
	v_exp_f32_e32 v118, v144
	v_add_f32_e32 v98, v112, v98
	v_exp_f32_e32 v119, v145
	v_add_f32_e32 v98, v113, v98
	v_exp_f32_e32 v120, v142
	v_add_f32_e32 v98, v116, v98
	v_exp_f32_e32 v121, v143
	v_add_f32_e32 v98, v117, v98
	v_exp_f32_e32 v122, v140
	v_add_f32_e32 v98, v118, v98
	v_exp_f32_e32 v123, v141
	v_add_f32_e32 v98, v119, v98
	v_add_f32_e32 v98, v120, v98
	v_add_f32_e32 v98, v121, v98
	v_add_f32_e32 v98, v122, v98
	v_add_f32_e32 v114, v123, v98
	v_mov_b32_e32 v115, v114
	v_cvt_pk_bf16_f32 v98, v146, v147
	v_cvt_pk_bf16_f32 v99, v148, v149
	v_cvt_pk_bf16_f32 v100, v154, v160
	v_cvt_pk_bf16_f32 v101, v161, v162
	v_cvt_pk_bf16_f32 v102, v151, v152
	v_cvt_pk_bf16_f32 v103, v153, v155
	v_cvt_pk_bf16_f32 v104, v156, v157
	v_cvt_pk_bf16_f32 v105, v158, v159
	v_cvt_pk_bf16_f32 v106, v106, v107
	v_cvt_pk_bf16_f32 v107, v108, v109
	v_cvt_pk_bf16_f32 v108, v110, v111
	v_cvt_pk_bf16_f32 v109, v112, v113
	v_cvt_pk_bf16_f32 v110, v116, v117
	v_cvt_pk_bf16_f32 v111, v118, v119
	v_cvt_pk_bf16_f32 v112, v120, v121
	v_cvt_pk_bf16_f32 v113, v122, v123
	v_permlane32_swap_b32_e32 v114, v115
	v_permlane32_swap_b32_e32 v98, v100
	v_permlane32_swap_b32_e32 v99, v101
	v_permlane32_swap_b32_e32 v102, v104
	v_permlane32_swap_b32_e32 v103, v105
	v_permlane32_swap_b32_e32 v106, v108
	v_permlane32_swap_b32_e32 v107, v109
	v_permlane32_swap_b32_e32 v110, v112
	v_permlane32_swap_b32_e32 v111, v113
	v_cmp_lt_i32_e32 vcc, 1, v184
	s_and_saveexec_b64 s[12:13], vcc
	s_cbranch_execz .LBB0_723
	ds_read_b64_tr_b16 v[116:117], v255 offset:0
	ds_read_b64_tr_b16 v[118:119], v255 offset:0x800
	ds_read_b64_tr_b16 v[120:121], v255 offset:0x1000
	ds_read_b64_tr_b16 v[122:123], v255 offset:0x1800
	ds_read_b64_tr_b16 v[124:125], v255 offset:0x2000
	ds_read_b64_tr_b16 v[126:127], v255 offset:0x2800
	ds_read_b64_tr_b16 v[128:129], v255 offset:0x3000
	ds_read_b64_tr_b16 v[130:131], v255 offset:0x3800
	s_waitcnt lgkmcnt(0)
	s_nop 0
	v_mfma_f32_32x32x16_bf16 v[2:17], v[98:101], v[116:119], v[2:17]
	ds_read_b64_tr_b16 v[116:117], v255 offset:0x200
	ds_read_b64_tr_b16 v[118:119], v255 offset:0xa00
	v_mfma_f32_32x32x16_bf16 v[2:17], v[102:105], v[120:123], v[2:17]
	ds_read_b64_tr_b16 v[120:121], v255 offset:0x1200
	ds_read_b64_tr_b16 v[122:123], v255 offset:0x1a00
	v_mfma_f32_32x32x16_bf16 v[2:17], v[106:109], v[124:127], v[2:17]
	ds_read_b64_tr_b16 v[124:125], v255 offset:0x2200
	ds_read_b64_tr_b16 v[126:127], v255 offset:0x2a00
	ds_read_b64_tr_b16 v[132:133], v255 offset:0x3200
	ds_read_b64_tr_b16 v[134:135], v255 offset:0x3a00
	s_waitcnt lgkmcnt(0)
	v_mfma_f32_32x32x16_bf16 v[2:17], v[110:113], v[128:131], v[2:17]
	v_mfma_f32_32x32x16_bf16 v[50:65], v[98:101], v[116:119], v[50:65]
	ds_read_b64_tr_b16 v[116:117], v255 offset:0x400
	ds_read_b64_tr_b16 v[118:119], v255 offset:0xc00
	v_mfma_f32_32x32x16_bf16 v[50:65], v[102:105], v[120:123], v[50:65]
	ds_read_b64_tr_b16 v[120:121], v255 offset:0x1400
	ds_read_b64_tr_b16 v[122:123], v255 offset:0x1c00
	v_mfma_f32_32x32x16_bf16 v[50:65], v[106:109], v[124:127], v[50:65]
	ds_read_b64_tr_b16 v[124:125], v255 offset:0x2400
	ds_read_b64_tr_b16 v[126:127], v255 offset:0x2c00
	ds_read_b64_tr_b16 v[128:129], v255 offset:0x3400
	ds_read_b64_tr_b16 v[130:131], v255 offset:0x3c00
	s_waitcnt lgkmcnt(0)
	v_mfma_f32_32x32x16_bf16 v[50:65], v[110:113], v[132:135], v[50:65]
	v_mfma_f32_32x32x16_bf16 v[34:49], v[98:101], v[116:119], v[34:49]
	ds_read_b64_tr_b16 v[116:117], v255 offset:0x600
	ds_read_b64_tr_b16 v[118:119], v255 offset:0xe00
	v_mfma_f32_32x32x16_bf16 v[34:49], v[102:105], v[120:123], v[34:49]
	ds_read_b64_tr_b16 v[120:121], v255 offset:0x1600
	ds_read_b64_tr_b16 v[122:123], v255 offset:0x1e00
	v_mfma_f32_32x32x16_bf16 v[34:49], v[106:109], v[124:127], v[34:49]
	ds_read_b64_tr_b16 v[124:125], v255 offset:0x2600
	ds_read_b64_tr_b16 v[126:127], v255 offset:0x2e00
	ds_read_b64_tr_b16 v[132:133], v255 offset:0x3600
	ds_read_b64_tr_b16 v[134:135], v255 offset:0x3e00
	s_waitcnt lgkmcnt(0)
	v_mfma_f32_32x32x16_bf16 v[34:49], v[110:113], v[128:131], v[34:49]
	v_mfma_f32_32x32x16_bf16 v[18:33], v[98:101], v[116:119], v[18:33]
	v_mfma_f32_32x32x16_bf16 v[18:33], v[102:105], v[120:123], v[18:33]
	v_mfma_f32_32x32x16_bf16 v[18:33], v[106:109], v[124:127], v[18:33]
	v_mfma_f32_32x32x16_bf16 v[18:33], v[110:113], v[132:135], v[18:33]

.LBB0_727:
	v_cndmask_b32_e64 v99, v99, v201, s[12:13]
	v_mul_f32_e32 v99, 0xbdd53b94, v99
	v_fmamk_f32 v100, v82, 0x3dd53b94, v99
	v_fmamk_f32 v101, v83, 0x3dd53b94, v99
	v_fmamk_f32 v82, v66, 0x3dd53b94, v99
	v_exp_f32_e32 v66, v100
	v_fmamk_f32 v84, v84, 0x3dd53b94, v99
	v_fmamk_f32 v83, v67, 0x3dd53b94, v99
	v_exp_f32_e32 v67, v101
	v_fmamk_f32 v85, v85, 0x3dd53b94, v99
	v_fmamk_f32 v102, v87, 0x3dd53b94, v99
	v_fmamk_f32 v87, v68, 0x3dd53b94, v99
	v_exp_f32_e32 v68, v84
	v_fmamk_f32 v86, v86, 0x3dd53b94, v99
	v_fmamk_f32 v103, v88, 0x3dd53b94, v99
	v_fmamk_f32 v88, v69, 0x3dd53b94, v99
	v_exp_f32_e32 v69, v85
	v_fmamk_f32 v79, v79, 0x3dd53b94, v99
	v_fmamk_f32 v111, v96, 0x3dd53b94, v99
	v_fmamk_f32 v96, v77, 0x3dd53b94, v99
	v_exp_f32_e32 v77, v86
	v_exp_f32_e32 v101, v79
	v_add_f32_e32 v79, 0, v66
	v_exp_f32_e32 v84, v102
	v_add_f32_e32 v79, v67, v79
	v_fmamk_f32 v104, v89, 0x3dd53b94, v99
	v_exp_f32_e32 v85, v103
	v_add_f32_e32 v79, v68, v79
	v_fmamk_f32 v105, v90, 0x3dd53b94, v99
	v_exp_f32_e32 v86, v104
	v_add_f32_e32 v79, v69, v79
	v_fmamk_f32 v106, v91, 0x3dd53b94, v99
	v_fmamk_f32 v89, v70, 0x3dd53b94, v99
	v_exp_f32_e32 v70, v105
	v_add_f32_e32 v79, v77, v79
	v_fmamk_f32 v107, v92, 0x3dd53b94, v99
	v_fmamk_f32 v90, v71, 0x3dd53b94, v99
	v_exp_f32_e32 v71, v106
	v_add_f32_e32 v79, v84, v79
	v_fmamk_f32 v108, v93, 0x3dd53b94, v99
	v_fmamk_f32 v91, v72, 0x3dd53b94, v99
	v_exp_f32_e32 v72, v107
	v_add_f32_e32 v79, v85, v79
	v_fmamk_f32 v109, v94, 0x3dd53b94, v99
	v_fmamk_f32 v92, v73, 0x3dd53b94, v99
	v_exp_f32_e32 v73, v108
	v_add_f32_e32 v79, v86, v79
	v_fmamk_f32 v110, v95, 0x3dd53b94, v99
	v_fmamk_f32 v93, v74, 0x3dd53b94, v99
	v_exp_f32_e32 v74, v109
	v_add_f32_e32 v79, v70, v79
	v_fmamk_f32 v94, v75, 0x3dd53b94, v99
	v_exp_f32_e32 v75, v110
	v_add_f32_e32 v79, v71, v79
	v_fmamk_f32 v112, v97, 0x3dd53b94, v99
	v_fmamk_f32 v95, v76, 0x3dd53b94, v99
	v_exp_f32_e32 v76, v111
	v_add_f32_e32 v79, v72, v79
	v_fmamk_f32 v97, v78, 0x3dd53b94, v99
	v_exp_f32_e32 v78, v112
	v_add_f32_e32 v79, v73, v79
	v_fmamk_f32 v80, v80, 0x3dd53b94, v99
	v_fmac_f32_e32 v99, 0x3dd53b94, v81
	v_exp_f32_e32 v81, v82
	v_add_f32_e32 v79, v74, v79
	v_exp_f32_e32 v100, v83
	v_add_f32_e32 v79, v75, v79
	v_exp_f32_e32 v87, v87
	v_add_f32_e32 v79, v76, v79
	v_exp_f32_e32 v88, v88
	v_add_f32_e32 v79, v78, v79
	v_exp_f32_e32 v89, v89
	v_add_f32_e32 v79, v81, v79
	v_exp_f32_e32 v90, v90
	v_add_f32_e32 v79, v100, v79
	v_exp_f32_e32 v91, v91
	v_add_f32_e32 v79, v87, v79
	v_exp_f32_e32 v92, v92
	v_add_f32_e32 v79, v88, v79
	v_exp_f32_e32 v93, v93
	v_add_f32_e32 v79, v89, v79
	v_exp_f32_e32 v94, v94
	v_add_f32_e32 v79, v90, v79
	v_exp_f32_e32 v95, v95
	v_add_f32_e32 v79, v91, v79
	v_exp_f32_e32 v96, v96
	v_add_f32_e32 v79, v92, v79
	v_exp_f32_e32 v97, v97
	v_add_f32_e32 v79, v93, v79
	v_add_f32_e32 v79, v94, v79
	v_exp_f32_e32 v102, v80
	v_add_f32_e32 v79, v95, v79
	v_exp_f32_e32 v99, v99
	v_add_f32_e32 v79, v96, v79
	v_add_f32_e32 v79, v97, v79
	v_add_f32_e32 v79, v101, v79
	v_add_f32_e32 v79, v102, v79
	v_add_f32_e32 v82, v99, v79
	v_mov_b32_e32 v83, v82
	v_cvt_pk_bf16_f32 v66, v66, v67
	v_cvt_pk_bf16_f32 v67, v68, v69
	v_cvt_pk_bf16_f32 v68, v77, v84
	v_cvt_pk_bf16_f32 v69, v85, v86
	v_cvt_pk_bf16_f32 v70, v70, v71
	v_cvt_pk_bf16_f32 v71, v72, v73
	v_cvt_pk_bf16_f32 v72, v74, v75
	v_cvt_pk_bf16_f32 v73, v76, v78
	v_cvt_pk_bf16_f32 v74, v81, v100
	v_cvt_pk_bf16_f32 v75, v87, v88
	v_cvt_pk_bf16_f32 v76, v89, v90
	v_cvt_pk_bf16_f32 v77, v91, v92
	v_cvt_pk_bf16_f32 v78, v93, v94
	v_cvt_pk_bf16_f32 v79, v95, v96
	v_cvt_pk_bf16_f32 v80, v97, v101
	v_cvt_pk_bf16_f32 v81, v102, v99
	v_permlane32_swap_b32_e32 v82, v83
	v_permlane32_swap_b32_e32 v66, v68
	v_permlane32_swap_b32_e32 v67, v69
	v_permlane32_swap_b32_e32 v70, v72
	v_permlane32_swap_b32_e32 v71, v73
	v_permlane32_swap_b32_e32 v74, v76
	v_permlane32_swap_b32_e32 v75, v77
	v_permlane32_swap_b32_e32 v78, v80
	v_permlane32_swap_b32_e32 v79, v81
	s_and_saveexec_b64 s[12:13], s[10:11]
	s_cbranch_execz .LBB0_729
	ds_read_b64_tr_b16 v[84:85], v254 offset:0
	ds_read_b64_tr_b16 v[86:87], v254 offset:0x800
	ds_read_b64_tr_b16 v[88:89], v254 offset:0x1000
	ds_read_b64_tr_b16 v[90:91], v254 offset:0x1800
	ds_read_b64_tr_b16 v[92:93], v254 offset:0x2000
	ds_read_b64_tr_b16 v[94:95], v254 offset:0x2800
	ds_read_b64_tr_b16 v[100:101], v254 offset:0x3000
	ds_read_b64_tr_b16 v[102:103], v254 offset:0x3800
	s_waitcnt lgkmcnt(0)
	s_nop 0
	v_mfma_f32_32x32x16_bf16 v[2:17], v[66:69], v[84:87], v[2:17]
	ds_read_b64_tr_b16 v[84:85], v254 offset:0x200
	ds_read_b64_tr_b16 v[86:87], v254 offset:0xa00
	v_mfma_f32_32x32x16_bf16 v[2:17], v[70:73], v[88:91], v[2:17]
	ds_read_b64_tr_b16 v[88:89], v254 offset:0x1200
	ds_read_b64_tr_b16 v[90:91], v254 offset:0x1a00
	v_mfma_f32_32x32x16_bf16 v[2:17], v[74:77], v[92:95], v[2:17]
	ds_read_b64_tr_b16 v[92:93], v254 offset:0x2200
	ds_read_b64_tr_b16 v[94:95], v254 offset:0x2a00
	ds_read_b64_tr_b16 v[104:105], v254 offset:0x3200
	ds_read_b64_tr_b16 v[106:107], v254 offset:0x3a00
	s_waitcnt lgkmcnt(0)
	v_mfma_f32_32x32x16_bf16 v[2:17], v[78:81], v[100:103], v[2:17]
	v_mfma_f32_32x32x16_bf16 v[50:65], v[66:69], v[84:87], v[50:65]
	ds_read_b64_tr_b16 v[84:85], v254 offset:0x400
	ds_read_b64_tr_b16 v[86:87], v254 offset:0xc00
	v_mfma_f32_32x32x16_bf16 v[50:65], v[70:73], v[88:91], v[50:65]
	ds_read_b64_tr_b16 v[88:89], v254 offset:0x1400
	ds_read_b64_tr_b16 v[90:91], v254 offset:0x1c00
	v_mfma_f32_32x32x16_bf16 v[50:65], v[74:77], v[92:95], v[50:65]
	ds_read_b64_tr_b16 v[92:93], v254 offset:0x2400
	ds_read_b64_tr_b16 v[94:95], v254 offset:0x2c00
	ds_read_b64_tr_b16 v[100:101], v254 offset:0x3400
	ds_read_b64_tr_b16 v[102:103], v254 offset:0x3c00
	s_waitcnt lgkmcnt(0)
	v_mfma_f32_32x32x16_bf16 v[50:65], v[78:81], v[104:107], v[50:65]
	v_mfma_f32_32x32x16_bf16 v[34:49], v[66:69], v[84:87], v[34:49]
	ds_read_b64_tr_b16 v[84:85], v254 offset:0x600
	ds_read_b64_tr_b16 v[86:87], v254 offset:0xe00
	v_mfma_f32_32x32x16_bf16 v[34:49], v[70:73], v[88:91], v[34:49]
	ds_read_b64_tr_b16 v[88:89], v254 offset:0x1600
	ds_read_b64_tr_b16 v[90:91], v254 offset:0x1e00
	v_mfma_f32_32x32x16_bf16 v[34:49], v[74:77], v[92:95], v[34:49]
	ds_read_b64_tr_b16 v[92:93], v254 offset:0x2600
	ds_read_b64_tr_b16 v[94:95], v254 offset:0x2e00
	ds_read_b64_tr_b16 v[104:105], v254 offset:0x3600
	ds_read_b64_tr_b16 v[106:107], v254 offset:0x3e00
	s_waitcnt lgkmcnt(0)
	v_mfma_f32_32x32x16_bf16 v[34:49], v[78:81], v[100:103], v[34:49]
	v_mfma_f32_32x32x16_bf16 v[18:33], v[66:69], v[84:87], v[18:33]
	v_mfma_f32_32x32x16_bf16 v[18:33], v[70:73], v[88:91], v[18:33]
	v_mfma_f32_32x32x16_bf16 v[18:33], v[74:77], v[92:95], v[18:33]
	v_mfma_f32_32x32x16_bf16 v[18:33], v[78:81], v[104:107], v[18:33]
